# v10 plus hand-scheduled VALU partial-dot (gdot) loops: 2-ahead index loads, 1-ahead gathers, bank-masked DPP transposing reduction
# speedup vs baseline: 1.0108x; 1.0108x over previous
.LBB0_532:
	s_or_b64 exec, exec, s[0:1]
	s_waitcnt lgkmcnt(0)
	v_mov_b32_e32 v0, v178
	s_and_b32 s5, s88, -8
	s_barrier
	s_and_b32 s4, s88, 7
	v_ashrrev_i32_e32 v1, 6, v0
	v_writelane_b32 v255, s5, 3
	v_add_u32_e32 v152, s5, v1
	s_lshl_b32 s92, s4, 14
	v_writelane_b32 v255, s4, 4
	s_lshl_b32 s4, s4, 21
	s_movk_i32 s16, 0x4000
	s_mov_b64 s[2:3], 0
	s_mov_b64 s[0:1], 0
	s_and_b32 s89, s90, -8
	s_mov_b32 s93, 0
	v_writelane_b32 v255, s4, 5
	v_cmp_gt_i32_e32 vcc, s16, v152
	s_and_saveexec_b64 s[10:11], vcc
	s_cbranch_execz .LBB0_541
	v_readlane_b32 s0, v254, 0
	v_readlane_b32 s1, v254, 1
	v_readlane_b32 s34, v255, 4
	s_lshl_b32 s35, s34, 21
	s_add_u32 s2, s0, 0x2120000
	s_addc_u32 s3, s1, 0
	s_add_u32 s2, s2, s35
	s_addc_u32 s3, s3, 0
	v_readlane_b32 s4, v254, 39
	v_readlane_b32 s5, v254, 40
	s_lshl_b32 s35, s34, 9
	s_add_u32 s4, s4, s35
	s_addc_u32 s5, s5, 0
	s_add_u32 s6, s0, 0x19d20000
	s_addc_u32 s7, s1, 0
	s_lshl_b32 s35, s34, 23
	s_add_u32 s12, s0, 0x10120000
	s_addc_u32 s13, s1, 0
	s_add_u32 s12, s12, s35
	s_addc_u32 s13, s13, 0
	v_readfirstlane_b32 s20, v178
	s_lshr_b32 s20, s20, 6
	v_readlane_b32 s35, v255, 3
	s_add_u32 s20, s20, s35
	s_and_b32 s21, s90, -8
	v_and_b32_e32 v176, 7, v179
	v_lshlrev_b32_e32 v177, 6, v176
	v_lshlrev_b32_e32 v176, 4, v176
	v_lshlrev_b32_e32 v180, 3, v179
	v_lshrrev_b32_e32 v181, 3, v179
	v_lshlrev_b32_e32 v181, 6, v181
	s_mov_b32 s26, 0xcccccccc
	s_mov_b32 s27, 0xcccccccc
	s_mov_b32 s28, 0xaaaaaaaa
	s_mov_b32 s29, 0xaaaaaaaa
	s_lshl_b32 s34, s20, 9
	s_add_u32 s22, s6, s34
	s_addc_u32 s23, s7, 0
	global_load_dwordx4 v[160:163], v181, s[22:23] offset:0
	global_load_dwordx4 v[164:167], v181, s[22:23] offset:16
	global_load_dwordx4 v[168:171], v181, s[22:23] offset:32
	global_load_dwordx4 v[172:175], v181, s[22:23] offset:48
	s_add_u32 s36, s20, s21
	s_min_u32 s36, s36, 0x3fff
	s_lshl_b32 s34, s36, 9
	s_add_u32 s22, s6, s34
	s_addc_u32 s23, s7, 0
	global_load_dwordx4 v[186:189], v181, s[22:23] offset:0
	global_load_dwordx4 v[190:193], v181, s[22:23] offset:16
	global_load_dwordx4 v[194:197], v181, s[22:23] offset:32
	global_load_dwordx4 v[198:201], v181, s[22:23] offset:48
	s_waitcnt vmcnt(0)
	v_lshl_or_b32 v160, v160, 7, v176
	v_lshl_or_b32 v161, v161, 7, v176
	v_lshl_or_b32 v162, v162, 7, v176
	v_lshl_or_b32 v163, v163, 7, v176
	v_lshl_or_b32 v164, v164, 7, v176
	v_lshl_or_b32 v165, v165, 7, v176
	v_lshl_or_b32 v166, v166, 7, v176
	v_lshl_or_b32 v167, v167, 7, v176
	v_lshl_or_b32 v168, v168, 7, v176
	v_lshl_or_b32 v169, v169, 7, v176
	v_lshl_or_b32 v170, v170, 7, v176
	v_lshl_or_b32 v171, v171, 7, v176
	v_lshl_or_b32 v172, v172, 7, v176
	v_lshl_or_b32 v173, v173, 7, v176
	v_lshl_or_b32 v174, v174, 7, v176
	v_lshl_or_b32 v175, v175, 7, v176
	s_lshl_b32 s34, s20, 12
	s_add_u32 s24, s4, s34
	s_addc_u32 s25, s5, 0
	global_load_dwordx4 v[128:131], v177, s[24:25] offset:0
	global_load_dwordx4 v[132:135], v177, s[24:25] offset:16
	global_load_dwordx4 v[136:139], v177, s[24:25] offset:32
	global_load_dwordx4 v[140:143], v177, s[24:25] offset:48
	global_load_dwordx4 v[0:3], v160, s[2:3]
	global_load_dwordx4 v[4:7], v161, s[2:3]
	global_load_dwordx4 v[8:11], v162, s[2:3]
	global_load_dwordx4 v[12:15], v163, s[2:3]
	global_load_dwordx4 v[16:19], v164, s[2:3]
	global_load_dwordx4 v[20:23], v165, s[2:3]
	global_load_dwordx4 v[24:27], v166, s[2:3]
	global_load_dwordx4 v[28:31], v167, s[2:3]
	global_load_dwordx4 v[32:35], v168, s[2:3]
	global_load_dwordx4 v[36:39], v169, s[2:3]
	global_load_dwordx4 v[40:43], v170, s[2:3]
	global_load_dwordx4 v[44:47], v171, s[2:3]
	global_load_dwordx4 v[48:51], v172, s[2:3]
	global_load_dwordx4 v[52:55], v173, s[2:3]
	global_load_dwordx4 v[56:59], v174, s[2:3]
	global_load_dwordx4 v[60:63], v175, s[2:3]
	s_add_u32 s37, s36, s21
	s_min_u32 s37, s37, 0x3fff
	s_lshl_b32 s34, s37, 9
	s_add_u32 s22, s6, s34
	s_addc_u32 s23, s7, 0
	global_load_dwordx4 v[234:237], v181, s[22:23] offset:0
	global_load_dwordx4 v[238:241], v181, s[22:23] offset:16
	global_load_dwordx4 v[242:245], v181, s[22:23] offset:32
	global_load_dwordx4 v[246:249], v181, s[22:23] offset:48
	global_load_dword v250, v180, s[22:23]
.Lgd_loop_L0:
	s_add_u32 s36, s20, s21
	s_add_u32 s37, s36, s21
	s_add_u32 s37, s37, s21
	s_min_u32 s36, s36, 0x3fff
	s_min_u32 s37, s37, 0x3fff
	s_waitcnt vmcnt(25)
	v_lshl_or_b32 v186, v186, 7, v176
	v_lshl_or_b32 v187, v187, 7, v176
	v_lshl_or_b32 v188, v188, 7, v176
	v_lshl_or_b32 v189, v189, 7, v176
	v_lshl_or_b32 v190, v190, 7, v176
	v_lshl_or_b32 v191, v191, 7, v176
	v_lshl_or_b32 v192, v192, 7, v176
	v_lshl_or_b32 v193, v193, 7, v176
	v_lshl_or_b32 v194, v194, 7, v176
	v_lshl_or_b32 v195, v195, 7, v176
	v_lshl_or_b32 v196, v196, 7, v176
	v_lshl_or_b32 v197, v197, 7, v176
	v_lshl_or_b32 v198, v198, 7, v176
	v_lshl_or_b32 v199, v199, 7, v176
	v_lshl_or_b32 v200, v200, 7, v176
	v_lshl_or_b32 v201, v201, 7, v176
	s_lshl_b32 s34, s36, 12
	s_add_u32 s24, s4, s34
	s_addc_u32 s25, s5, 0
	global_load_dwordx4 v[144:147], v177, s[24:25] offset:0
	global_load_dwordx4 v[148:151], v177, s[24:25] offset:16
	global_load_dwordx4 v[152:155], v177, s[24:25] offset:32
	global_load_dwordx4 v[156:159], v177, s[24:25] offset:48
	global_load_dwordx4 v[64:67], v186, s[2:3]
	global_load_dwordx4 v[68:71], v187, s[2:3]
	global_load_dwordx4 v[72:75], v188, s[2:3]
	global_load_dwordx4 v[76:79], v189, s[2:3]
	global_load_dwordx4 v[80:83], v190, s[2:3]
	global_load_dwordx4 v[84:87], v191, s[2:3]
	global_load_dwordx4 v[88:91], v192, s[2:3]
	global_load_dwordx4 v[92:95], v193, s[2:3]
	global_load_dwordx4 v[96:99], v194, s[2:3]
	global_load_dwordx4 v[100:103], v195, s[2:3]
	global_load_dwordx4 v[104:107], v196, s[2:3]
	global_load_dwordx4 v[108:111], v197, s[2:3]
	global_load_dwordx4 v[112:115], v198, s[2:3]
	global_load_dwordx4 v[116:119], v199, s[2:3]
	global_load_dwordx4 v[120:123], v200, s[2:3]
	global_load_dwordx4 v[124:127], v201, s[2:3]
	s_lshl_b32 s34, s37, 9
	s_add_u32 s22, s6, s34
	s_addc_u32 s23, s7, 0
	global_load_dwordx4 v[160:163], v181, s[22:23] offset:0
	global_load_dwordx4 v[164:167], v181, s[22:23] offset:16
	global_load_dwordx4 v[168:171], v181, s[22:23] offset:32
	global_load_dwordx4 v[172:175], v181, s[22:23] offset:48
	s_waitcnt vmcnt(29)
	v_cvt_pk_f32_fp8_e32 v[218:219], v0
	v_cvt_pk_f32_fp8_e32 v[226:227], v4
	v_cvt_pk_f32_fp8_sdwa v[220:221], v0 src0_sel:WORD_1
	v_cvt_pk_f32_fp8_sdwa v[228:229], v4 src0_sel:WORD_1
	v_cvt_pk_f32_fp8_e32 v[222:223], v1
	v_cvt_pk_f32_fp8_e32 v[230:231], v5
	v_cvt_pk_f32_fp8_sdwa v[224:225], v1 src0_sel:WORD_1
	v_cvt_pk_f32_fp8_sdwa v[232:233], v5 src0_sel:WORD_1
	v_pk_mul_f32 v[250:251], v[218:219], v[128:129]
	v_pk_mul_f32 v[252:253], v[226:227], v[128:129]
	v_pk_fma_f32 v[250:251], v[220:221], v[130:131], v[250:251]
	v_pk_fma_f32 v[252:253], v[228:229], v[130:131], v[252:253]
	v_pk_fma_f32 v[250:251], v[222:223], v[132:133], v[250:251]
	v_pk_fma_f32 v[252:253], v[230:231], v[132:133], v[252:253]
	v_pk_fma_f32 v[250:251], v[224:225], v[134:135], v[250:251]
	v_pk_fma_f32 v[252:253], v[232:233], v[134:135], v[252:253]
	v_cvt_pk_f32_fp8_e32 v[218:219], v2
	v_cvt_pk_f32_fp8_e32 v[226:227], v6
	v_cvt_pk_f32_fp8_sdwa v[220:221], v2 src0_sel:WORD_1
	v_cvt_pk_f32_fp8_sdwa v[228:229], v6 src0_sel:WORD_1
	v_cvt_pk_f32_fp8_e32 v[222:223], v3
	v_cvt_pk_f32_fp8_e32 v[230:231], v7
	v_cvt_pk_f32_fp8_sdwa v[224:225], v3 src0_sel:WORD_1
	v_cvt_pk_f32_fp8_sdwa v[232:233], v7 src0_sel:WORD_1
	v_pk_fma_f32 v[250:251], v[218:219], v[136:137], v[250:251]
	v_pk_fma_f32 v[252:253], v[226:227], v[136:137], v[252:253]
	v_pk_fma_f32 v[250:251], v[220:221], v[138:139], v[250:251]
	v_pk_fma_f32 v[252:253], v[228:229], v[138:139], v[252:253]
	v_pk_fma_f32 v[250:251], v[222:223], v[140:141], v[250:251]
	v_pk_fma_f32 v[252:253], v[230:231], v[140:141], v[252:253]
	v_pk_fma_f32 v[250:251], v[224:225], v[142:143], v[250:251]
	v_pk_fma_f32 v[252:253], v[232:233], v[142:143], v[252:253]
	v_add_f32_e32 v202, v250, v251
	v_add_f32_e32 v203, v252, v253
	v_cvt_pk_f32_fp8_e32 v[218:219], v8
	v_cvt_pk_f32_fp8_e32 v[226:227], v12
	v_cvt_pk_f32_fp8_sdwa v[220:221], v8 src0_sel:WORD_1
	v_cvt_pk_f32_fp8_sdwa v[228:229], v12 src0_sel:WORD_1
	v_cvt_pk_f32_fp8_e32 v[222:223], v9
	v_cvt_pk_f32_fp8_e32 v[230:231], v13
	v_cvt_pk_f32_fp8_sdwa v[224:225], v9 src0_sel:WORD_1
	v_cvt_pk_f32_fp8_sdwa v[232:233], v13 src0_sel:WORD_1
	v_pk_mul_f32 v[250:251], v[218:219], v[128:129]
	v_pk_mul_f32 v[252:253], v[226:227], v[128:129]
	v_pk_fma_f32 v[250:251], v[220:221], v[130:131], v[250:251]
	v_pk_fma_f32 v[252:253], v[228:229], v[130:131], v[252:253]
	v_pk_fma_f32 v[250:251], v[222:223], v[132:133], v[250:251]
	v_pk_fma_f32 v[252:253], v[230:231], v[132:133], v[252:253]
	v_pk_fma_f32 v[250:251], v[224:225], v[134:135], v[250:251]
	v_pk_fma_f32 v[252:253], v[232:233], v[134:135], v[252:253]
	v_cvt_pk_f32_fp8_e32 v[218:219], v10
	v_cvt_pk_f32_fp8_e32 v[226:227], v14
	v_cvt_pk_f32_fp8_sdwa v[220:221], v10 src0_sel:WORD_1
	v_cvt_pk_f32_fp8_sdwa v[228:229], v14 src0_sel:WORD_1
	v_cvt_pk_f32_fp8_e32 v[222:223], v11
	v_cvt_pk_f32_fp8_e32 v[230:231], v15
	v_cvt_pk_f32_fp8_sdwa v[224:225], v11 src0_sel:WORD_1
	v_cvt_pk_f32_fp8_sdwa v[232:233], v15 src0_sel:WORD_1
	v_pk_fma_f32 v[250:251], v[218:219], v[136:137], v[250:251]
	v_pk_fma_f32 v[252:253], v[226:227], v[136:137], v[252:253]
	v_pk_fma_f32 v[250:251], v[220:221], v[138:139], v[250:251]
	v_pk_fma_f32 v[252:253], v[228:229], v[138:139], v[252:253]
	v_pk_fma_f32 v[250:251], v[222:223], v[140:141], v[250:251]
	v_pk_fma_f32 v[252:253], v[230:231], v[140:141], v[252:253]
	v_pk_fma_f32 v[250:251], v[224:225], v[142:143], v[250:251]
	v_pk_fma_f32 v[252:253], v[232:233], v[142:143], v[252:253]
	v_add_f32_e32 v204, v250, v251
	v_add_f32_e32 v205, v252, v253
	v_cvt_pk_f32_fp8_e32 v[218:219], v16
	v_cvt_pk_f32_fp8_e32 v[226:227], v20
	v_cvt_pk_f32_fp8_sdwa v[220:221], v16 src0_sel:WORD_1
	v_cvt_pk_f32_fp8_sdwa v[228:229], v20 src0_sel:WORD_1
	v_cvt_pk_f32_fp8_e32 v[222:223], v17
	v_cvt_pk_f32_fp8_e32 v[230:231], v21
	v_cvt_pk_f32_fp8_sdwa v[224:225], v17 src0_sel:WORD_1
	v_cvt_pk_f32_fp8_sdwa v[232:233], v21 src0_sel:WORD_1
	v_pk_mul_f32 v[250:251], v[218:219], v[128:129]
	v_pk_mul_f32 v[252:253], v[226:227], v[128:129]
	v_pk_fma_f32 v[250:251], v[220:221], v[130:131], v[250:251]
	v_pk_fma_f32 v[252:253], v[228:229], v[130:131], v[252:253]
	v_pk_fma_f32 v[250:251], v[222:223], v[132:133], v[250:251]
	v_pk_fma_f32 v[252:253], v[230:231], v[132:133], v[252:253]
	v_pk_fma_f32 v[250:251], v[224:225], v[134:135], v[250:251]
	v_pk_fma_f32 v[252:253], v[232:233], v[134:135], v[252:253]
	v_cvt_pk_f32_fp8_e32 v[218:219], v18
	v_cvt_pk_f32_fp8_e32 v[226:227], v22
	v_cvt_pk_f32_fp8_sdwa v[220:221], v18 src0_sel:WORD_1
	v_cvt_pk_f32_fp8_sdwa v[228:229], v22 src0_sel:WORD_1
	v_cvt_pk_f32_fp8_e32 v[222:223], v19
	v_cvt_pk_f32_fp8_e32 v[230:231], v23
	v_cvt_pk_f32_fp8_sdwa v[224:225], v19 src0_sel:WORD_1
	v_cvt_pk_f32_fp8_sdwa v[232:233], v23 src0_sel:WORD_1
	v_pk_fma_f32 v[250:251], v[218:219], v[136:137], v[250:251]
	v_pk_fma_f32 v[252:253], v[226:227], v[136:137], v[252:253]
	v_pk_fma_f32 v[250:251], v[220:221], v[138:139], v[250:251]
	v_pk_fma_f32 v[252:253], v[228:229], v[138:139], v[252:253]
	v_pk_fma_f32 v[250:251], v[222:223], v[140:141], v[250:251]
	v_pk_fma_f32 v[252:253], v[230:231], v[140:141], v[252:253]
	v_pk_fma_f32 v[250:251], v[224:225], v[142:143], v[250:251]
	v_pk_fma_f32 v[252:253], v[232:233], v[142:143], v[252:253]
	v_add_f32_e32 v206, v250, v251
	v_add_f32_e32 v207, v252, v253
	v_cvt_pk_f32_fp8_e32 v[218:219], v24
	v_cvt_pk_f32_fp8_e32 v[226:227], v28
	v_cvt_pk_f32_fp8_sdwa v[220:221], v24 src0_sel:WORD_1
	v_cvt_pk_f32_fp8_sdwa v[228:229], v28 src0_sel:WORD_1
	v_cvt_pk_f32_fp8_e32 v[222:223], v25
	v_cvt_pk_f32_fp8_e32 v[230:231], v29
	v_cvt_pk_f32_fp8_sdwa v[224:225], v25 src0_sel:WORD_1
	v_cvt_pk_f32_fp8_sdwa v[232:233], v29 src0_sel:WORD_1
	v_pk_mul_f32 v[250:251], v[218:219], v[128:129]
	v_pk_mul_f32 v[252:253], v[226:227], v[128:129]
	v_pk_fma_f32 v[250:251], v[220:221], v[130:131], v[250:251]
	v_pk_fma_f32 v[252:253], v[228:229], v[130:131], v[252:253]
	v_pk_fma_f32 v[250:251], v[222:223], v[132:133], v[250:251]
	v_pk_fma_f32 v[252:253], v[230:231], v[132:133], v[252:253]
	v_pk_fma_f32 v[250:251], v[224:225], v[134:135], v[250:251]
	v_pk_fma_f32 v[252:253], v[232:233], v[134:135], v[252:253]
	v_cvt_pk_f32_fp8_e32 v[218:219], v26
	v_cvt_pk_f32_fp8_e32 v[226:227], v30
	v_cvt_pk_f32_fp8_sdwa v[220:221], v26 src0_sel:WORD_1
	v_cvt_pk_f32_fp8_sdwa v[228:229], v30 src0_sel:WORD_1
	v_cvt_pk_f32_fp8_e32 v[222:223], v27
	v_cvt_pk_f32_fp8_e32 v[230:231], v31
	v_cvt_pk_f32_fp8_sdwa v[224:225], v27 src0_sel:WORD_1
	v_cvt_pk_f32_fp8_sdwa v[232:233], v31 src0_sel:WORD_1
	v_pk_fma_f32 v[250:251], v[218:219], v[136:137], v[250:251]
	v_pk_fma_f32 v[252:253], v[226:227], v[136:137], v[252:253]
	v_pk_fma_f32 v[250:251], v[220:221], v[138:139], v[250:251]
	v_pk_fma_f32 v[252:253], v[228:229], v[138:139], v[252:253]
	v_pk_fma_f32 v[250:251], v[222:223], v[140:141], v[250:251]
	v_pk_fma_f32 v[252:253], v[230:231], v[140:141], v[252:253]
	v_pk_fma_f32 v[250:251], v[224:225], v[142:143], v[250:251]
	v_pk_fma_f32 v[252:253], v[232:233], v[142:143], v[252:253]
	v_add_f32_e32 v208, v250, v251
	v_add_f32_e32 v209, v252, v253
	v_cvt_pk_f32_fp8_e32 v[218:219], v32
	v_cvt_pk_f32_fp8_e32 v[226:227], v36
	v_cvt_pk_f32_fp8_sdwa v[220:221], v32 src0_sel:WORD_1
	v_cvt_pk_f32_fp8_sdwa v[228:229], v36 src0_sel:WORD_1
	v_cvt_pk_f32_fp8_e32 v[222:223], v33
	v_cvt_pk_f32_fp8_e32 v[230:231], v37
	v_cvt_pk_f32_fp8_sdwa v[224:225], v33 src0_sel:WORD_1
	v_cvt_pk_f32_fp8_sdwa v[232:233], v37 src0_sel:WORD_1
	v_pk_mul_f32 v[250:251], v[218:219], v[128:129]
	v_pk_mul_f32 v[252:253], v[226:227], v[128:129]
	v_pk_fma_f32 v[250:251], v[220:221], v[130:131], v[250:251]
	v_pk_fma_f32 v[252:253], v[228:229], v[130:131], v[252:253]
	v_pk_fma_f32 v[250:251], v[222:223], v[132:133], v[250:251]
	v_pk_fma_f32 v[252:253], v[230:231], v[132:133], v[252:253]
	v_pk_fma_f32 v[250:251], v[224:225], v[134:135], v[250:251]
	v_pk_fma_f32 v[252:253], v[232:233], v[134:135], v[252:253]
	v_cvt_pk_f32_fp8_e32 v[218:219], v34
	v_cvt_pk_f32_fp8_e32 v[226:227], v38
	v_cvt_pk_f32_fp8_sdwa v[220:221], v34 src0_sel:WORD_1
	v_cvt_pk_f32_fp8_sdwa v[228:229], v38 src0_sel:WORD_1
	v_cvt_pk_f32_fp8_e32 v[222:223], v35
	v_cvt_pk_f32_fp8_e32 v[230:231], v39
	v_cvt_pk_f32_fp8_sdwa v[224:225], v35 src0_sel:WORD_1
	v_cvt_pk_f32_fp8_sdwa v[232:233], v39 src0_sel:WORD_1
	v_pk_fma_f32 v[250:251], v[218:219], v[136:137], v[250:251]
	v_pk_fma_f32 v[252:253], v[226:227], v[136:137], v[252:253]
	v_pk_fma_f32 v[250:251], v[220:221], v[138:139], v[250:251]
	v_pk_fma_f32 v[252:253], v[228:229], v[138:139], v[252:253]
	v_pk_fma_f32 v[250:251], v[222:223], v[140:141], v[250:251]
	v_pk_fma_f32 v[252:253], v[230:231], v[140:141], v[252:253]
	v_pk_fma_f32 v[250:251], v[224:225], v[142:143], v[250:251]
	v_pk_fma_f32 v[252:253], v[232:233], v[142:143], v[252:253]
	v_add_f32_e32 v210, v250, v251
	v_add_f32_e32 v211, v252, v253
	v_cvt_pk_f32_fp8_e32 v[218:219], v40
	v_cvt_pk_f32_fp8_e32 v[226:227], v44
	v_cvt_pk_f32_fp8_sdwa v[220:221], v40 src0_sel:WORD_1
	v_cvt_pk_f32_fp8_sdwa v[228:229], v44 src0_sel:WORD_1
	v_cvt_pk_f32_fp8_e32 v[222:223], v41
	v_cvt_pk_f32_fp8_e32 v[230:231], v45
	v_cvt_pk_f32_fp8_sdwa v[224:225], v41 src0_sel:WORD_1
	v_cvt_pk_f32_fp8_sdwa v[232:233], v45 src0_sel:WORD_1
	v_pk_mul_f32 v[250:251], v[218:219], v[128:129]
	v_pk_mul_f32 v[252:253], v[226:227], v[128:129]
	v_pk_fma_f32 v[250:251], v[220:221], v[130:131], v[250:251]
	v_pk_fma_f32 v[252:253], v[228:229], v[130:131], v[252:253]
	v_pk_fma_f32 v[250:251], v[222:223], v[132:133], v[250:251]
	v_pk_fma_f32 v[252:253], v[230:231], v[132:133], v[252:253]
	v_pk_fma_f32 v[250:251], v[224:225], v[134:135], v[250:251]
	v_pk_fma_f32 v[252:253], v[232:233], v[134:135], v[252:253]
	v_cvt_pk_f32_fp8_e32 v[218:219], v42
	v_cvt_pk_f32_fp8_e32 v[226:227], v46
	v_cvt_pk_f32_fp8_sdwa v[220:221], v42 src0_sel:WORD_1
	v_cvt_pk_f32_fp8_sdwa v[228:229], v46 src0_sel:WORD_1
	v_cvt_pk_f32_fp8_e32 v[222:223], v43
	v_cvt_pk_f32_fp8_e32 v[230:231], v47
	v_cvt_pk_f32_fp8_sdwa v[224:225], v43 src0_sel:WORD_1
	v_cvt_pk_f32_fp8_sdwa v[232:233], v47 src0_sel:WORD_1
	v_pk_fma_f32 v[250:251], v[218:219], v[136:137], v[250:251]
	v_pk_fma_f32 v[252:253], v[226:227], v[136:137], v[252:253]
	v_pk_fma_f32 v[250:251], v[220:221], v[138:139], v[250:251]
	v_pk_fma_f32 v[252:253], v[228:229], v[138:139], v[252:253]
	v_pk_fma_f32 v[250:251], v[222:223], v[140:141], v[250:251]
	v_pk_fma_f32 v[252:253], v[230:231], v[140:141], v[252:253]
	v_pk_fma_f32 v[250:251], v[224:225], v[142:143], v[250:251]
	v_pk_fma_f32 v[252:253], v[232:233], v[142:143], v[252:253]
	v_add_f32_e32 v212, v250, v251
	v_add_f32_e32 v213, v252, v253
	v_cvt_pk_f32_fp8_e32 v[218:219], v48
	v_cvt_pk_f32_fp8_e32 v[226:227], v52
	v_cvt_pk_f32_fp8_sdwa v[220:221], v48 src0_sel:WORD_1
	v_cvt_pk_f32_fp8_sdwa v[228:229], v52 src0_sel:WORD_1
	v_cvt_pk_f32_fp8_e32 v[222:223], v49
	v_cvt_pk_f32_fp8_e32 v[230:231], v53
	v_cvt_pk_f32_fp8_sdwa v[224:225], v49 src0_sel:WORD_1
	v_cvt_pk_f32_fp8_sdwa v[232:233], v53 src0_sel:WORD_1
	v_pk_mul_f32 v[250:251], v[218:219], v[128:129]
	v_pk_mul_f32 v[252:253], v[226:227], v[128:129]
	v_pk_fma_f32 v[250:251], v[220:221], v[130:131], v[250:251]
	v_pk_fma_f32 v[252:253], v[228:229], v[130:131], v[252:253]
	v_pk_fma_f32 v[250:251], v[222:223], v[132:133], v[250:251]
	v_pk_fma_f32 v[252:253], v[230:231], v[132:133], v[252:253]
	v_pk_fma_f32 v[250:251], v[224:225], v[134:135], v[250:251]
	v_pk_fma_f32 v[252:253], v[232:233], v[134:135], v[252:253]
	v_cvt_pk_f32_fp8_e32 v[218:219], v50
	v_cvt_pk_f32_fp8_e32 v[226:227], v54
	v_cvt_pk_f32_fp8_sdwa v[220:221], v50 src0_sel:WORD_1
	v_cvt_pk_f32_fp8_sdwa v[228:229], v54 src0_sel:WORD_1
	v_cvt_pk_f32_fp8_e32 v[222:223], v51
	v_cvt_pk_f32_fp8_e32 v[230:231], v55
	v_cvt_pk_f32_fp8_sdwa v[224:225], v51 src0_sel:WORD_1
	v_cvt_pk_f32_fp8_sdwa v[232:233], v55 src0_sel:WORD_1
	v_pk_fma_f32 v[250:251], v[218:219], v[136:137], v[250:251]
	v_pk_fma_f32 v[252:253], v[226:227], v[136:137], v[252:253]
	v_pk_fma_f32 v[250:251], v[220:221], v[138:139], v[250:251]
	v_pk_fma_f32 v[252:253], v[228:229], v[138:139], v[252:253]
	v_pk_fma_f32 v[250:251], v[222:223], v[140:141], v[250:251]
	v_pk_fma_f32 v[252:253], v[230:231], v[140:141], v[252:253]
	v_pk_fma_f32 v[250:251], v[224:225], v[142:143], v[250:251]
	v_pk_fma_f32 v[252:253], v[232:233], v[142:143], v[252:253]
	v_add_f32_e32 v214, v250, v251
	v_add_f32_e32 v215, v252, v253
	v_cvt_pk_f32_fp8_e32 v[218:219], v56
	v_cvt_pk_f32_fp8_e32 v[226:227], v60
	v_cvt_pk_f32_fp8_sdwa v[220:221], v56 src0_sel:WORD_1
	v_cvt_pk_f32_fp8_sdwa v[228:229], v60 src0_sel:WORD_1
	v_cvt_pk_f32_fp8_e32 v[222:223], v57
	v_cvt_pk_f32_fp8_e32 v[230:231], v61
	v_cvt_pk_f32_fp8_sdwa v[224:225], v57 src0_sel:WORD_1
	v_cvt_pk_f32_fp8_sdwa v[232:233], v61 src0_sel:WORD_1
	v_pk_mul_f32 v[250:251], v[218:219], v[128:129]
	v_pk_mul_f32 v[252:253], v[226:227], v[128:129]
	v_pk_fma_f32 v[250:251], v[220:221], v[130:131], v[250:251]
	v_pk_fma_f32 v[252:253], v[228:229], v[130:131], v[252:253]
	v_pk_fma_f32 v[250:251], v[222:223], v[132:133], v[250:251]
	v_pk_fma_f32 v[252:253], v[230:231], v[132:133], v[252:253]
	v_pk_fma_f32 v[250:251], v[224:225], v[134:135], v[250:251]
	v_pk_fma_f32 v[252:253], v[232:233], v[134:135], v[252:253]
	v_cvt_pk_f32_fp8_e32 v[218:219], v58
	v_cvt_pk_f32_fp8_e32 v[226:227], v62
	v_cvt_pk_f32_fp8_sdwa v[220:221], v58 src0_sel:WORD_1
	v_cvt_pk_f32_fp8_sdwa v[228:229], v62 src0_sel:WORD_1
	v_cvt_pk_f32_fp8_e32 v[222:223], v59
	v_cvt_pk_f32_fp8_e32 v[230:231], v63
	v_cvt_pk_f32_fp8_sdwa v[224:225], v59 src0_sel:WORD_1
	v_cvt_pk_f32_fp8_sdwa v[232:233], v63 src0_sel:WORD_1
	v_pk_fma_f32 v[250:251], v[218:219], v[136:137], v[250:251]
	v_pk_fma_f32 v[252:253], v[226:227], v[136:137], v[252:253]
	v_pk_fma_f32 v[250:251], v[220:221], v[138:139], v[250:251]
	v_pk_fma_f32 v[252:253], v[228:229], v[138:139], v[252:253]
	v_pk_fma_f32 v[250:251], v[222:223], v[140:141], v[250:251]
	v_pk_fma_f32 v[252:253], v[230:231], v[140:141], v[252:253]
	v_pk_fma_f32 v[250:251], v[224:225], v[142:143], v[250:251]
	v_pk_fma_f32 v[252:253], v[232:233], v[142:143], v[252:253]
	v_add_f32_e32 v216, v250, v251
	v_add_f32_e32 v217, v252, v253
	s_lshl_b32 s34, s20, 9
	s_add_u32 s32, s12, s34
	s_addc_u32 s33, s13, 0
	s_nop 1
	v_add_f32_dpp v218, v202, v202 row_half_mirror row_mask:0xf bank_mask:0x5
	v_add_f32_dpp v219, v203, v203 row_half_mirror row_mask:0xf bank_mask:0x5
	v_add_f32_dpp v220, v204, v204 row_half_mirror row_mask:0xf bank_mask:0x5
	v_add_f32_dpp v221, v205, v205 row_half_mirror row_mask:0xf bank_mask:0x5
	v_add_f32_dpp v222, v206, v206 row_half_mirror row_mask:0xf bank_mask:0x5
	v_add_f32_dpp v223, v207, v207 row_half_mirror row_mask:0xf bank_mask:0x5
	v_add_f32_dpp v224, v208, v208 row_half_mirror row_mask:0xf bank_mask:0x5
	v_add_f32_dpp v225, v209, v209 row_half_mirror row_mask:0xf bank_mask:0x5
	v_add_f32_dpp v218, v210, v210 row_half_mirror row_mask:0xf bank_mask:0xa
	v_add_f32_dpp v219, v211, v211 row_half_mirror row_mask:0xf bank_mask:0xa
	v_add_f32_dpp v220, v212, v212 row_half_mirror row_mask:0xf bank_mask:0xa
	v_add_f32_dpp v221, v213, v213 row_half_mirror row_mask:0xf bank_mask:0xa
	v_add_f32_dpp v222, v214, v214 row_half_mirror row_mask:0xf bank_mask:0xa
	v_add_f32_dpp v223, v215, v215 row_half_mirror row_mask:0xf bank_mask:0xa
	v_add_f32_dpp v224, v216, v216 row_half_mirror row_mask:0xf bank_mask:0xa
	v_add_f32_dpp v225, v217, v217 row_half_mirror row_mask:0xf bank_mask:0xa
	v_cndmask_b32_e64 v226, v218, v222, s[26:27]
	v_cndmask_b32_e64 v227, v219, v223, s[26:27]
	v_cndmask_b32_e64 v228, v220, v224, s[26:27]
	v_cndmask_b32_e64 v229, v221, v225, s[26:27]
	v_cndmask_b32_e64 v230, v222, v218, s[26:27]
	v_cndmask_b32_e64 v231, v223, v219, s[26:27]
	v_cndmask_b32_e64 v232, v224, v220, s[26:27]
	v_cndmask_b32_e64 v233, v225, v221, s[26:27]
	s_nop 0
	v_add_f32_dpp v250, v230, v226 quad_perm:[2,3,0,1] row_mask:0xf bank_mask:0xf
	v_add_f32_dpp v251, v231, v227 quad_perm:[2,3,0,1] row_mask:0xf bank_mask:0xf
	v_add_f32_dpp v252, v232, v228 quad_perm:[2,3,0,1] row_mask:0xf bank_mask:0xf
	v_add_f32_dpp v253, v233, v229 quad_perm:[2,3,0,1] row_mask:0xf bank_mask:0xf
	v_cndmask_b32_e64 v226, v250, v252, s[28:29]
	v_cndmask_b32_e64 v227, v251, v253, s[28:29]
	v_cndmask_b32_e64 v230, v252, v250, s[28:29]
	v_cndmask_b32_e64 v231, v253, v251, s[28:29]
	s_nop 1
	v_add_f32_dpp v218, v230, v226 quad_perm:[1,0,3,2] row_mask:0xf bank_mask:0xf
	v_add_f32_dpp v219, v231, v227 quad_perm:[1,0,3,2] row_mask:0xf bank_mask:0xf
	global_store_dwordx2 v180, v[218:219], s[32:33]
	s_add_u32 s20, s20, s21
	s_cmp_lt_u32 s20, 0x4000
	s_cbranch_scc0 .Lgd_done_L0
	s_add_u32 s36, s20, s21
	s_add_u32 s37, s36, s21
	s_add_u32 s37, s37, s21
	s_min_u32 s36, s36, 0x3fff
	s_min_u32 s37, s37, 0x3fff
	s_waitcnt vmcnt(25)
	v_lshl_or_b32 v234, v234, 7, v176
	v_lshl_or_b32 v235, v235, 7, v176
	v_lshl_or_b32 v236, v236, 7, v176
	v_lshl_or_b32 v237, v237, 7, v176
	v_lshl_or_b32 v238, v238, 7, v176
	v_lshl_or_b32 v239, v239, 7, v176
	v_lshl_or_b32 v240, v240, 7, v176
	v_lshl_or_b32 v241, v241, 7, v176
	v_lshl_or_b32 v242, v242, 7, v176
	v_lshl_or_b32 v243, v243, 7, v176
	v_lshl_or_b32 v244, v244, 7, v176
	v_lshl_or_b32 v245, v245, 7, v176
	v_lshl_or_b32 v246, v246, 7, v176
	v_lshl_or_b32 v247, v247, 7, v176
	v_lshl_or_b32 v248, v248, 7, v176
	v_lshl_or_b32 v249, v249, 7, v176
	s_lshl_b32 s34, s36, 12
	s_add_u32 s24, s4, s34
	s_addc_u32 s25, s5, 0
	global_load_dwordx4 v[128:131], v177, s[24:25] offset:0
	global_load_dwordx4 v[132:135], v177, s[24:25] offset:16
	global_load_dwordx4 v[136:139], v177, s[24:25] offset:32
	global_load_dwordx4 v[140:143], v177, s[24:25] offset:48
	global_load_dwordx4 v[0:3], v234, s[2:3]
	global_load_dwordx4 v[4:7], v235, s[2:3]
	global_load_dwordx4 v[8:11], v236, s[2:3]
	global_load_dwordx4 v[12:15], v237, s[2:3]
	global_load_dwordx4 v[16:19], v238, s[2:3]
	global_load_dwordx4 v[20:23], v239, s[2:3]
	global_load_dwordx4 v[24:27], v240, s[2:3]
	global_load_dwordx4 v[28:31], v241, s[2:3]
	global_load_dwordx4 v[32:35], v242, s[2:3]
	global_load_dwordx4 v[36:39], v243, s[2:3]
	global_load_dwordx4 v[40:43], v244, s[2:3]
	global_load_dwordx4 v[44:47], v245, s[2:3]
	global_load_dwordx4 v[48:51], v246, s[2:3]
	global_load_dwordx4 v[52:55], v247, s[2:3]
	global_load_dwordx4 v[56:59], v248, s[2:3]
	global_load_dwordx4 v[60:63], v249, s[2:3]
	s_lshl_b32 s34, s37, 9
	s_add_u32 s22, s6, s34
	s_addc_u32 s23, s7, 0
	global_load_dwordx4 v[186:189], v181, s[22:23] offset:0
	global_load_dwordx4 v[190:193], v181, s[22:23] offset:16
	global_load_dwordx4 v[194:197], v181, s[22:23] offset:32
	global_load_dwordx4 v[198:201], v181, s[22:23] offset:48
	s_waitcnt vmcnt(29)
	v_cvt_pk_f32_fp8_e32 v[218:219], v64
	v_cvt_pk_f32_fp8_e32 v[226:227], v68
	v_cvt_pk_f32_fp8_sdwa v[220:221], v64 src0_sel:WORD_1
	v_cvt_pk_f32_fp8_sdwa v[228:229], v68 src0_sel:WORD_1
	v_cvt_pk_f32_fp8_e32 v[222:223], v65
	v_cvt_pk_f32_fp8_e32 v[230:231], v69
	v_cvt_pk_f32_fp8_sdwa v[224:225], v65 src0_sel:WORD_1
	v_cvt_pk_f32_fp8_sdwa v[232:233], v69 src0_sel:WORD_1
	v_pk_mul_f32 v[250:251], v[218:219], v[144:145]
	v_pk_mul_f32 v[252:253], v[226:227], v[144:145]
	v_pk_fma_f32 v[250:251], v[220:221], v[146:147], v[250:251]
	v_pk_fma_f32 v[252:253], v[228:229], v[146:147], v[252:253]
	v_pk_fma_f32 v[250:251], v[222:223], v[148:149], v[250:251]
	v_pk_fma_f32 v[252:253], v[230:231], v[148:149], v[252:253]
	v_pk_fma_f32 v[250:251], v[224:225], v[150:151], v[250:251]
	v_pk_fma_f32 v[252:253], v[232:233], v[150:151], v[252:253]
	v_cvt_pk_f32_fp8_e32 v[218:219], v66
	v_cvt_pk_f32_fp8_e32 v[226:227], v70
	v_cvt_pk_f32_fp8_sdwa v[220:221], v66 src0_sel:WORD_1
	v_cvt_pk_f32_fp8_sdwa v[228:229], v70 src0_sel:WORD_1
	v_cvt_pk_f32_fp8_e32 v[222:223], v67
	v_cvt_pk_f32_fp8_e32 v[230:231], v71
	v_cvt_pk_f32_fp8_sdwa v[224:225], v67 src0_sel:WORD_1
	v_cvt_pk_f32_fp8_sdwa v[232:233], v71 src0_sel:WORD_1
	v_pk_fma_f32 v[250:251], v[218:219], v[152:153], v[250:251]
	v_pk_fma_f32 v[252:253], v[226:227], v[152:153], v[252:253]
	v_pk_fma_f32 v[250:251], v[220:221], v[154:155], v[250:251]
	v_pk_fma_f32 v[252:253], v[228:229], v[154:155], v[252:253]
	v_pk_fma_f32 v[250:251], v[222:223], v[156:157], v[250:251]
	v_pk_fma_f32 v[252:253], v[230:231], v[156:157], v[252:253]
	v_pk_fma_f32 v[250:251], v[224:225], v[158:159], v[250:251]
	v_pk_fma_f32 v[252:253], v[232:233], v[158:159], v[252:253]
	v_add_f32_e32 v202, v250, v251
	v_add_f32_e32 v203, v252, v253
	v_cvt_pk_f32_fp8_e32 v[218:219], v72
	v_cvt_pk_f32_fp8_e32 v[226:227], v76
	v_cvt_pk_f32_fp8_sdwa v[220:221], v72 src0_sel:WORD_1
	v_cvt_pk_f32_fp8_sdwa v[228:229], v76 src0_sel:WORD_1
	v_cvt_pk_f32_fp8_e32 v[222:223], v73
	v_cvt_pk_f32_fp8_e32 v[230:231], v77
	v_cvt_pk_f32_fp8_sdwa v[224:225], v73 src0_sel:WORD_1
	v_cvt_pk_f32_fp8_sdwa v[232:233], v77 src0_sel:WORD_1
	v_pk_mul_f32 v[250:251], v[218:219], v[144:145]
	v_pk_mul_f32 v[252:253], v[226:227], v[144:145]
	v_pk_fma_f32 v[250:251], v[220:221], v[146:147], v[250:251]
	v_pk_fma_f32 v[252:253], v[228:229], v[146:147], v[252:253]
	v_pk_fma_f32 v[250:251], v[222:223], v[148:149], v[250:251]
	v_pk_fma_f32 v[252:253], v[230:231], v[148:149], v[252:253]
	v_pk_fma_f32 v[250:251], v[224:225], v[150:151], v[250:251]
	v_pk_fma_f32 v[252:253], v[232:233], v[150:151], v[252:253]
	v_cvt_pk_f32_fp8_e32 v[218:219], v74
	v_cvt_pk_f32_fp8_e32 v[226:227], v78
	v_cvt_pk_f32_fp8_sdwa v[220:221], v74 src0_sel:WORD_1
	v_cvt_pk_f32_fp8_sdwa v[228:229], v78 src0_sel:WORD_1
	v_cvt_pk_f32_fp8_e32 v[222:223], v75
	v_cvt_pk_f32_fp8_e32 v[230:231], v79
	v_cvt_pk_f32_fp8_sdwa v[224:225], v75 src0_sel:WORD_1
	v_cvt_pk_f32_fp8_sdwa v[232:233], v79 src0_sel:WORD_1
	v_pk_fma_f32 v[250:251], v[218:219], v[152:153], v[250:251]
	v_pk_fma_f32 v[252:253], v[226:227], v[152:153], v[252:253]
	v_pk_fma_f32 v[250:251], v[220:221], v[154:155], v[250:251]
	v_pk_fma_f32 v[252:253], v[228:229], v[154:155], v[252:253]
	v_pk_fma_f32 v[250:251], v[222:223], v[156:157], v[250:251]
	v_pk_fma_f32 v[252:253], v[230:231], v[156:157], v[252:253]
	v_pk_fma_f32 v[250:251], v[224:225], v[158:159], v[250:251]
	v_pk_fma_f32 v[252:253], v[232:233], v[158:159], v[252:253]
	v_add_f32_e32 v204, v250, v251
	v_add_f32_e32 v205, v252, v253
	v_cvt_pk_f32_fp8_e32 v[218:219], v80
	v_cvt_pk_f32_fp8_e32 v[226:227], v84
	v_cvt_pk_f32_fp8_sdwa v[220:221], v80 src0_sel:WORD_1
	v_cvt_pk_f32_fp8_sdwa v[228:229], v84 src0_sel:WORD_1
	v_cvt_pk_f32_fp8_e32 v[222:223], v81
	v_cvt_pk_f32_fp8_e32 v[230:231], v85
	v_cvt_pk_f32_fp8_sdwa v[224:225], v81 src0_sel:WORD_1
	v_cvt_pk_f32_fp8_sdwa v[232:233], v85 src0_sel:WORD_1
	v_pk_mul_f32 v[250:251], v[218:219], v[144:145]
	v_pk_mul_f32 v[252:253], v[226:227], v[144:145]
	v_pk_fma_f32 v[250:251], v[220:221], v[146:147], v[250:251]
	v_pk_fma_f32 v[252:253], v[228:229], v[146:147], v[252:253]
	v_pk_fma_f32 v[250:251], v[222:223], v[148:149], v[250:251]
	v_pk_fma_f32 v[252:253], v[230:231], v[148:149], v[252:253]
	v_pk_fma_f32 v[250:251], v[224:225], v[150:151], v[250:251]
	v_pk_fma_f32 v[252:253], v[232:233], v[150:151], v[252:253]
	v_cvt_pk_f32_fp8_e32 v[218:219], v82
	v_cvt_pk_f32_fp8_e32 v[226:227], v86
	v_cvt_pk_f32_fp8_sdwa v[220:221], v82 src0_sel:WORD_1
	v_cvt_pk_f32_fp8_sdwa v[228:229], v86 src0_sel:WORD_1
	v_cvt_pk_f32_fp8_e32 v[222:223], v83
	v_cvt_pk_f32_fp8_e32 v[230:231], v87
	v_cvt_pk_f32_fp8_sdwa v[224:225], v83 src0_sel:WORD_1
	v_cvt_pk_f32_fp8_sdwa v[232:233], v87 src0_sel:WORD_1
	v_pk_fma_f32 v[250:251], v[218:219], v[152:153], v[250:251]
	v_pk_fma_f32 v[252:253], v[226:227], v[152:153], v[252:253]
	v_pk_fma_f32 v[250:251], v[220:221], v[154:155], v[250:251]
	v_pk_fma_f32 v[252:253], v[228:229], v[154:155], v[252:253]
	v_pk_fma_f32 v[250:251], v[222:223], v[156:157], v[250:251]
	v_pk_fma_f32 v[252:253], v[230:231], v[156:157], v[252:253]
	v_pk_fma_f32 v[250:251], v[224:225], v[158:159], v[250:251]
	v_pk_fma_f32 v[252:253], v[232:233], v[158:159], v[252:253]
	v_add_f32_e32 v206, v250, v251
	v_add_f32_e32 v207, v252, v253
	v_cvt_pk_f32_fp8_e32 v[218:219], v88
	v_cvt_pk_f32_fp8_e32 v[226:227], v92
	v_cvt_pk_f32_fp8_sdwa v[220:221], v88 src0_sel:WORD_1
	v_cvt_pk_f32_fp8_sdwa v[228:229], v92 src0_sel:WORD_1
	v_cvt_pk_f32_fp8_e32 v[222:223], v89
	v_cvt_pk_f32_fp8_e32 v[230:231], v93
	v_cvt_pk_f32_fp8_sdwa v[224:225], v89 src0_sel:WORD_1
	v_cvt_pk_f32_fp8_sdwa v[232:233], v93 src0_sel:WORD_1
	v_pk_mul_f32 v[250:251], v[218:219], v[144:145]
	v_pk_mul_f32 v[252:253], v[226:227], v[144:145]
	v_pk_fma_f32 v[250:251], v[220:221], v[146:147], v[250:251]
	v_pk_fma_f32 v[252:253], v[228:229], v[146:147], v[252:253]
	v_pk_fma_f32 v[250:251], v[222:223], v[148:149], v[250:251]
	v_pk_fma_f32 v[252:253], v[230:231], v[148:149], v[252:253]
	v_pk_fma_f32 v[250:251], v[224:225], v[150:151], v[250:251]
	v_pk_fma_f32 v[252:253], v[232:233], v[150:151], v[252:253]
	v_cvt_pk_f32_fp8_e32 v[218:219], v90
	v_cvt_pk_f32_fp8_e32 v[226:227], v94
	v_cvt_pk_f32_fp8_sdwa v[220:221], v90 src0_sel:WORD_1
	v_cvt_pk_f32_fp8_sdwa v[228:229], v94 src0_sel:WORD_1
	v_cvt_pk_f32_fp8_e32 v[222:223], v91
	v_cvt_pk_f32_fp8_e32 v[230:231], v95
	v_cvt_pk_f32_fp8_sdwa v[224:225], v91 src0_sel:WORD_1
	v_cvt_pk_f32_fp8_sdwa v[232:233], v95 src0_sel:WORD_1
	v_pk_fma_f32 v[250:251], v[218:219], v[152:153], v[250:251]
	v_pk_fma_f32 v[252:253], v[226:227], v[152:153], v[252:253]
	v_pk_fma_f32 v[250:251], v[220:221], v[154:155], v[250:251]
	v_pk_fma_f32 v[252:253], v[228:229], v[154:155], v[252:253]
	v_pk_fma_f32 v[250:251], v[222:223], v[156:157], v[250:251]
	v_pk_fma_f32 v[252:253], v[230:231], v[156:157], v[252:253]
	v_pk_fma_f32 v[250:251], v[224:225], v[158:159], v[250:251]
	v_pk_fma_f32 v[252:253], v[232:233], v[158:159], v[252:253]
	v_add_f32_e32 v208, v250, v251
	v_add_f32_e32 v209, v252, v253
	v_cvt_pk_f32_fp8_e32 v[218:219], v96
	v_cvt_pk_f32_fp8_e32 v[226:227], v100
	v_cvt_pk_f32_fp8_sdwa v[220:221], v96 src0_sel:WORD_1
	v_cvt_pk_f32_fp8_sdwa v[228:229], v100 src0_sel:WORD_1
	v_cvt_pk_f32_fp8_e32 v[222:223], v97
	v_cvt_pk_f32_fp8_e32 v[230:231], v101
	v_cvt_pk_f32_fp8_sdwa v[224:225], v97 src0_sel:WORD_1
	v_cvt_pk_f32_fp8_sdwa v[232:233], v101 src0_sel:WORD_1
	v_pk_mul_f32 v[250:251], v[218:219], v[144:145]
	v_pk_mul_f32 v[252:253], v[226:227], v[144:145]
	v_pk_fma_f32 v[250:251], v[220:221], v[146:147], v[250:251]
	v_pk_fma_f32 v[252:253], v[228:229], v[146:147], v[252:253]
	v_pk_fma_f32 v[250:251], v[222:223], v[148:149], v[250:251]
	v_pk_fma_f32 v[252:253], v[230:231], v[148:149], v[252:253]
	v_pk_fma_f32 v[250:251], v[224:225], v[150:151], v[250:251]
	v_pk_fma_f32 v[252:253], v[232:233], v[150:151], v[252:253]
	v_cvt_pk_f32_fp8_e32 v[218:219], v98
	v_cvt_pk_f32_fp8_e32 v[226:227], v102
	v_cvt_pk_f32_fp8_sdwa v[220:221], v98 src0_sel:WORD_1
	v_cvt_pk_f32_fp8_sdwa v[228:229], v102 src0_sel:WORD_1
	v_cvt_pk_f32_fp8_e32 v[222:223], v99
	v_cvt_pk_f32_fp8_e32 v[230:231], v103
	v_cvt_pk_f32_fp8_sdwa v[224:225], v99 src0_sel:WORD_1
	v_cvt_pk_f32_fp8_sdwa v[232:233], v103 src0_sel:WORD_1
	v_pk_fma_f32 v[250:251], v[218:219], v[152:153], v[250:251]
	v_pk_fma_f32 v[252:253], v[226:227], v[152:153], v[252:253]
	v_pk_fma_f32 v[250:251], v[220:221], v[154:155], v[250:251]
	v_pk_fma_f32 v[252:253], v[228:229], v[154:155], v[252:253]
	v_pk_fma_f32 v[250:251], v[222:223], v[156:157], v[250:251]
	v_pk_fma_f32 v[252:253], v[230:231], v[156:157], v[252:253]
	v_pk_fma_f32 v[250:251], v[224:225], v[158:159], v[250:251]
	v_pk_fma_f32 v[252:253], v[232:233], v[158:159], v[252:253]
	v_add_f32_e32 v210, v250, v251
	v_add_f32_e32 v211, v252, v253
	v_cvt_pk_f32_fp8_e32 v[218:219], v104
	v_cvt_pk_f32_fp8_e32 v[226:227], v108
	v_cvt_pk_f32_fp8_sdwa v[220:221], v104 src0_sel:WORD_1
	v_cvt_pk_f32_fp8_sdwa v[228:229], v108 src0_sel:WORD_1
	v_cvt_pk_f32_fp8_e32 v[222:223], v105
	v_cvt_pk_f32_fp8_e32 v[230:231], v109
	v_cvt_pk_f32_fp8_sdwa v[224:225], v105 src0_sel:WORD_1
	v_cvt_pk_f32_fp8_sdwa v[232:233], v109 src0_sel:WORD_1
	v_pk_mul_f32 v[250:251], v[218:219], v[144:145]
	v_pk_mul_f32 v[252:253], v[226:227], v[144:145]
	v_pk_fma_f32 v[250:251], v[220:221], v[146:147], v[250:251]
	v_pk_fma_f32 v[252:253], v[228:229], v[146:147], v[252:253]
	v_pk_fma_f32 v[250:251], v[222:223], v[148:149], v[250:251]
	v_pk_fma_f32 v[252:253], v[230:231], v[148:149], v[252:253]
	v_pk_fma_f32 v[250:251], v[224:225], v[150:151], v[250:251]
	v_pk_fma_f32 v[252:253], v[232:233], v[150:151], v[252:253]
	v_cvt_pk_f32_fp8_e32 v[218:219], v106
	v_cvt_pk_f32_fp8_e32 v[226:227], v110
	v_cvt_pk_f32_fp8_sdwa v[220:221], v106 src0_sel:WORD_1
	v_cvt_pk_f32_fp8_sdwa v[228:229], v110 src0_sel:WORD_1
	v_cvt_pk_f32_fp8_e32 v[222:223], v107
	v_cvt_pk_f32_fp8_e32 v[230:231], v111
	v_cvt_pk_f32_fp8_sdwa v[224:225], v107 src0_sel:WORD_1
	v_cvt_pk_f32_fp8_sdwa v[232:233], v111 src0_sel:WORD_1
	v_pk_fma_f32 v[250:251], v[218:219], v[152:153], v[250:251]
	v_pk_fma_f32 v[252:253], v[226:227], v[152:153], v[252:253]
	v_pk_fma_f32 v[250:251], v[220:221], v[154:155], v[250:251]
	v_pk_fma_f32 v[252:253], v[228:229], v[154:155], v[252:253]
	v_pk_fma_f32 v[250:251], v[222:223], v[156:157], v[250:251]
	v_pk_fma_f32 v[252:253], v[230:231], v[156:157], v[252:253]
	v_pk_fma_f32 v[250:251], v[224:225], v[158:159], v[250:251]
	v_pk_fma_f32 v[252:253], v[232:233], v[158:159], v[252:253]
	v_add_f32_e32 v212, v250, v251
	v_add_f32_e32 v213, v252, v253
	v_cvt_pk_f32_fp8_e32 v[218:219], v112
	v_cvt_pk_f32_fp8_e32 v[226:227], v116
	v_cvt_pk_f32_fp8_sdwa v[220:221], v112 src0_sel:WORD_1
	v_cvt_pk_f32_fp8_sdwa v[228:229], v116 src0_sel:WORD_1
	v_cvt_pk_f32_fp8_e32 v[222:223], v113
	v_cvt_pk_f32_fp8_e32 v[230:231], v117
	v_cvt_pk_f32_fp8_sdwa v[224:225], v113 src0_sel:WORD_1
	v_cvt_pk_f32_fp8_sdwa v[232:233], v117 src0_sel:WORD_1
	v_pk_mul_f32 v[250:251], v[218:219], v[144:145]
	v_pk_mul_f32 v[252:253], v[226:227], v[144:145]
	v_pk_fma_f32 v[250:251], v[220:221], v[146:147], v[250:251]
	v_pk_fma_f32 v[252:253], v[228:229], v[146:147], v[252:253]
	v_pk_fma_f32 v[250:251], v[222:223], v[148:149], v[250:251]
	v_pk_fma_f32 v[252:253], v[230:231], v[148:149], v[252:253]
	v_pk_fma_f32 v[250:251], v[224:225], v[150:151], v[250:251]
	v_pk_fma_f32 v[252:253], v[232:233], v[150:151], v[252:253]
	v_cvt_pk_f32_fp8_e32 v[218:219], v114
	v_cvt_pk_f32_fp8_e32 v[226:227], v118
	v_cvt_pk_f32_fp8_sdwa v[220:221], v114 src0_sel:WORD_1
	v_cvt_pk_f32_fp8_sdwa v[228:229], v118 src0_sel:WORD_1
	v_cvt_pk_f32_fp8_e32 v[222:223], v115
	v_cvt_pk_f32_fp8_e32 v[230:231], v119
	v_cvt_pk_f32_fp8_sdwa v[224:225], v115 src0_sel:WORD_1
	v_cvt_pk_f32_fp8_sdwa v[232:233], v119 src0_sel:WORD_1
	v_pk_fma_f32 v[250:251], v[218:219], v[152:153], v[250:251]
	v_pk_fma_f32 v[252:253], v[226:227], v[152:153], v[252:253]
	v_pk_fma_f32 v[250:251], v[220:221], v[154:155], v[250:251]
	v_pk_fma_f32 v[252:253], v[228:229], v[154:155], v[252:253]
	v_pk_fma_f32 v[250:251], v[222:223], v[156:157], v[250:251]
	v_pk_fma_f32 v[252:253], v[230:231], v[156:157], v[252:253]
	v_pk_fma_f32 v[250:251], v[224:225], v[158:159], v[250:251]
	v_pk_fma_f32 v[252:253], v[232:233], v[158:159], v[252:253]
	v_add_f32_e32 v214, v250, v251
	v_add_f32_e32 v215, v252, v253
	v_cvt_pk_f32_fp8_e32 v[218:219], v120
	v_cvt_pk_f32_fp8_e32 v[226:227], v124
	v_cvt_pk_f32_fp8_sdwa v[220:221], v120 src0_sel:WORD_1
	v_cvt_pk_f32_fp8_sdwa v[228:229], v124 src0_sel:WORD_1
	v_cvt_pk_f32_fp8_e32 v[222:223], v121
	v_cvt_pk_f32_fp8_e32 v[230:231], v125
	v_cvt_pk_f32_fp8_sdwa v[224:225], v121 src0_sel:WORD_1
	v_cvt_pk_f32_fp8_sdwa v[232:233], v125 src0_sel:WORD_1
	v_pk_mul_f32 v[250:251], v[218:219], v[144:145]
	v_pk_mul_f32 v[252:253], v[226:227], v[144:145]
	v_pk_fma_f32 v[250:251], v[220:221], v[146:147], v[250:251]
	v_pk_fma_f32 v[252:253], v[228:229], v[146:147], v[252:253]
	v_pk_fma_f32 v[250:251], v[222:223], v[148:149], v[250:251]
	v_pk_fma_f32 v[252:253], v[230:231], v[148:149], v[252:253]
	v_pk_fma_f32 v[250:251], v[224:225], v[150:151], v[250:251]
	v_pk_fma_f32 v[252:253], v[232:233], v[150:151], v[252:253]
	v_cvt_pk_f32_fp8_e32 v[218:219], v122
	v_cvt_pk_f32_fp8_e32 v[226:227], v126
	v_cvt_pk_f32_fp8_sdwa v[220:221], v122 src0_sel:WORD_1
	v_cvt_pk_f32_fp8_sdwa v[228:229], v126 src0_sel:WORD_1
	v_cvt_pk_f32_fp8_e32 v[222:223], v123
	v_cvt_pk_f32_fp8_e32 v[230:231], v127
	v_cvt_pk_f32_fp8_sdwa v[224:225], v123 src0_sel:WORD_1
	v_cvt_pk_f32_fp8_sdwa v[232:233], v127 src0_sel:WORD_1
	v_pk_fma_f32 v[250:251], v[218:219], v[152:153], v[250:251]
	v_pk_fma_f32 v[252:253], v[226:227], v[152:153], v[252:253]
	v_pk_fma_f32 v[250:251], v[220:221], v[154:155], v[250:251]
	v_pk_fma_f32 v[252:253], v[228:229], v[154:155], v[252:253]
	v_pk_fma_f32 v[250:251], v[222:223], v[156:157], v[250:251]
	v_pk_fma_f32 v[252:253], v[230:231], v[156:157], v[252:253]
	v_pk_fma_f32 v[250:251], v[224:225], v[158:159], v[250:251]
	v_pk_fma_f32 v[252:253], v[232:233], v[158:159], v[252:253]
	v_add_f32_e32 v216, v250, v251
	v_add_f32_e32 v217, v252, v253
	s_lshl_b32 s34, s20, 9
	s_add_u32 s32, s12, s34
	s_addc_u32 s33, s13, 0
	s_nop 1
	v_add_f32_dpp v218, v202, v202 row_half_mirror row_mask:0xf bank_mask:0x5
	v_add_f32_dpp v219, v203, v203 row_half_mirror row_mask:0xf bank_mask:0x5
	v_add_f32_dpp v220, v204, v204 row_half_mirror row_mask:0xf bank_mask:0x5
	v_add_f32_dpp v221, v205, v205 row_half_mirror row_mask:0xf bank_mask:0x5
	v_add_f32_dpp v222, v206, v206 row_half_mirror row_mask:0xf bank_mask:0x5
	v_add_f32_dpp v223, v207, v207 row_half_mirror row_mask:0xf bank_mask:0x5
	v_add_f32_dpp v224, v208, v208 row_half_mirror row_mask:0xf bank_mask:0x5
	v_add_f32_dpp v225, v209, v209 row_half_mirror row_mask:0xf bank_mask:0x5
	v_add_f32_dpp v218, v210, v210 row_half_mirror row_mask:0xf bank_mask:0xa
	v_add_f32_dpp v219, v211, v211 row_half_mirror row_mask:0xf bank_mask:0xa
	v_add_f32_dpp v220, v212, v212 row_half_mirror row_mask:0xf bank_mask:0xa
	v_add_f32_dpp v221, v213, v213 row_half_mirror row_mask:0xf bank_mask:0xa
	v_add_f32_dpp v222, v214, v214 row_half_mirror row_mask:0xf bank_mask:0xa
	v_add_f32_dpp v223, v215, v215 row_half_mirror row_mask:0xf bank_mask:0xa
	v_add_f32_dpp v224, v216, v216 row_half_mirror row_mask:0xf bank_mask:0xa
	v_add_f32_dpp v225, v217, v217 row_half_mirror row_mask:0xf bank_mask:0xa
	v_cndmask_b32_e64 v226, v218, v222, s[26:27]
	v_cndmask_b32_e64 v227, v219, v223, s[26:27]
	v_cndmask_b32_e64 v228, v220, v224, s[26:27]
	v_cndmask_b32_e64 v229, v221, v225, s[26:27]
	v_cndmask_b32_e64 v230, v222, v218, s[26:27]
	v_cndmask_b32_e64 v231, v223, v219, s[26:27]
	v_cndmask_b32_e64 v232, v224, v220, s[26:27]
	v_cndmask_b32_e64 v233, v225, v221, s[26:27]
	s_nop 0
	v_add_f32_dpp v250, v230, v226 quad_perm:[2,3,0,1] row_mask:0xf bank_mask:0xf
	v_add_f32_dpp v251, v231, v227 quad_perm:[2,3,0,1] row_mask:0xf bank_mask:0xf
	v_add_f32_dpp v252, v232, v228 quad_perm:[2,3,0,1] row_mask:0xf bank_mask:0xf
	v_add_f32_dpp v253, v233, v229 quad_perm:[2,3,0,1] row_mask:0xf bank_mask:0xf
	v_cndmask_b32_e64 v226, v250, v252, s[28:29]
	v_cndmask_b32_e64 v227, v251, v253, s[28:29]
	v_cndmask_b32_e64 v230, v252, v250, s[28:29]
	v_cndmask_b32_e64 v231, v253, v251, s[28:29]
	s_nop 1
	v_add_f32_dpp v218, v230, v226 quad_perm:[1,0,3,2] row_mask:0xf bank_mask:0xf
	v_add_f32_dpp v219, v231, v227 quad_perm:[1,0,3,2] row_mask:0xf bank_mask:0xf
	global_store_dwordx2 v180, v[218:219], s[32:33]
	s_add_u32 s20, s20, s21
	s_cmp_lt_u32 s20, 0x4000
	s_cbranch_scc0 .Lgd_done_L0
	s_add_u32 s36, s20, s21
	s_add_u32 s37, s36, s21
	s_add_u32 s37, s37, s21
	s_min_u32 s36, s36, 0x3fff
	s_min_u32 s37, s37, 0x3fff
	s_waitcnt vmcnt(25)
	v_lshl_or_b32 v160, v160, 7, v176
	v_lshl_or_b32 v161, v161, 7, v176
	v_lshl_or_b32 v162, v162, 7, v176
	v_lshl_or_b32 v163, v163, 7, v176
	v_lshl_or_b32 v164, v164, 7, v176
	v_lshl_or_b32 v165, v165, 7, v176
	v_lshl_or_b32 v166, v166, 7, v176
	v_lshl_or_b32 v167, v167, 7, v176
	v_lshl_or_b32 v168, v168, 7, v176
	v_lshl_or_b32 v169, v169, 7, v176
	v_lshl_or_b32 v170, v170, 7, v176
	v_lshl_or_b32 v171, v171, 7, v176
	v_lshl_or_b32 v172, v172, 7, v176
	v_lshl_or_b32 v173, v173, 7, v176
	v_lshl_or_b32 v174, v174, 7, v176
	v_lshl_or_b32 v175, v175, 7, v176
	s_lshl_b32 s34, s36, 12
	s_add_u32 s24, s4, s34
	s_addc_u32 s25, s5, 0
	global_load_dwordx4 v[144:147], v177, s[24:25] offset:0
	global_load_dwordx4 v[148:151], v177, s[24:25] offset:16
	global_load_dwordx4 v[152:155], v177, s[24:25] offset:32
	global_load_dwordx4 v[156:159], v177, s[24:25] offset:48
	global_load_dwordx4 v[64:67], v160, s[2:3]
	global_load_dwordx4 v[68:71], v161, s[2:3]
	global_load_dwordx4 v[72:75], v162, s[2:3]
	global_load_dwordx4 v[76:79], v163, s[2:3]
	global_load_dwordx4 v[80:83], v164, s[2:3]
	global_load_dwordx4 v[84:87], v165, s[2:3]
	global_load_dwordx4 v[88:91], v166, s[2:3]
	global_load_dwordx4 v[92:95], v167, s[2:3]
	global_load_dwordx4 v[96:99], v168, s[2:3]
	global_load_dwordx4 v[100:103], v169, s[2:3]
	global_load_dwordx4 v[104:107], v170, s[2:3]
	global_load_dwordx4 v[108:111], v171, s[2:3]
	global_load_dwordx4 v[112:115], v172, s[2:3]
	global_load_dwordx4 v[116:119], v173, s[2:3]
	global_load_dwordx4 v[120:123], v174, s[2:3]
	global_load_dwordx4 v[124:127], v175, s[2:3]
	s_lshl_b32 s34, s37, 9
	s_add_u32 s22, s6, s34
	s_addc_u32 s23, s7, 0
	global_load_dwordx4 v[234:237], v181, s[22:23] offset:0
	global_load_dwordx4 v[238:241], v181, s[22:23] offset:16
	global_load_dwordx4 v[242:245], v181, s[22:23] offset:32
	global_load_dwordx4 v[246:249], v181, s[22:23] offset:48
	s_waitcnt vmcnt(29)
	v_cvt_pk_f32_fp8_e32 v[218:219], v0
	v_cvt_pk_f32_fp8_e32 v[226:227], v4
	v_cvt_pk_f32_fp8_sdwa v[220:221], v0 src0_sel:WORD_1
	v_cvt_pk_f32_fp8_sdwa v[228:229], v4 src0_sel:WORD_1
	v_cvt_pk_f32_fp8_e32 v[222:223], v1
	v_cvt_pk_f32_fp8_e32 v[230:231], v5
	v_cvt_pk_f32_fp8_sdwa v[224:225], v1 src0_sel:WORD_1
	v_cvt_pk_f32_fp8_sdwa v[232:233], v5 src0_sel:WORD_1
	v_pk_mul_f32 v[250:251], v[218:219], v[128:129]
	v_pk_mul_f32 v[252:253], v[226:227], v[128:129]
	v_pk_fma_f32 v[250:251], v[220:221], v[130:131], v[250:251]
	v_pk_fma_f32 v[252:253], v[228:229], v[130:131], v[252:253]
	v_pk_fma_f32 v[250:251], v[222:223], v[132:133], v[250:251]
	v_pk_fma_f32 v[252:253], v[230:231], v[132:133], v[252:253]
	v_pk_fma_f32 v[250:251], v[224:225], v[134:135], v[250:251]
	v_pk_fma_f32 v[252:253], v[232:233], v[134:135], v[252:253]
	v_cvt_pk_f32_fp8_e32 v[218:219], v2
	v_cvt_pk_f32_fp8_e32 v[226:227], v6
	v_cvt_pk_f32_fp8_sdwa v[220:221], v2 src0_sel:WORD_1
	v_cvt_pk_f32_fp8_sdwa v[228:229], v6 src0_sel:WORD_1
	v_cvt_pk_f32_fp8_e32 v[222:223], v3
	v_cvt_pk_f32_fp8_e32 v[230:231], v7
	v_cvt_pk_f32_fp8_sdwa v[224:225], v3 src0_sel:WORD_1
	v_cvt_pk_f32_fp8_sdwa v[232:233], v7 src0_sel:WORD_1
	v_pk_fma_f32 v[250:251], v[218:219], v[136:137], v[250:251]
	v_pk_fma_f32 v[252:253], v[226:227], v[136:137], v[252:253]
	v_pk_fma_f32 v[250:251], v[220:221], v[138:139], v[250:251]
	v_pk_fma_f32 v[252:253], v[228:229], v[138:139], v[252:253]
	v_pk_fma_f32 v[250:251], v[222:223], v[140:141], v[250:251]
	v_pk_fma_f32 v[252:253], v[230:231], v[140:141], v[252:253]
	v_pk_fma_f32 v[250:251], v[224:225], v[142:143], v[250:251]
	v_pk_fma_f32 v[252:253], v[232:233], v[142:143], v[252:253]
	v_add_f32_e32 v202, v250, v251
	v_add_f32_e32 v203, v252, v253
	v_cvt_pk_f32_fp8_e32 v[218:219], v8
	v_cvt_pk_f32_fp8_e32 v[226:227], v12
	v_cvt_pk_f32_fp8_sdwa v[220:221], v8 src0_sel:WORD_1
	v_cvt_pk_f32_fp8_sdwa v[228:229], v12 src0_sel:WORD_1
	v_cvt_pk_f32_fp8_e32 v[222:223], v9
	v_cvt_pk_f32_fp8_e32 v[230:231], v13
	v_cvt_pk_f32_fp8_sdwa v[224:225], v9 src0_sel:WORD_1
	v_cvt_pk_f32_fp8_sdwa v[232:233], v13 src0_sel:WORD_1
	v_pk_mul_f32 v[250:251], v[218:219], v[128:129]
	v_pk_mul_f32 v[252:253], v[226:227], v[128:129]
	v_pk_fma_f32 v[250:251], v[220:221], v[130:131], v[250:251]
	v_pk_fma_f32 v[252:253], v[228:229], v[130:131], v[252:253]
	v_pk_fma_f32 v[250:251], v[222:223], v[132:133], v[250:251]
	v_pk_fma_f32 v[252:253], v[230:231], v[132:133], v[252:253]
	v_pk_fma_f32 v[250:251], v[224:225], v[134:135], v[250:251]
	v_pk_fma_f32 v[252:253], v[232:233], v[134:135], v[252:253]
	v_cvt_pk_f32_fp8_e32 v[218:219], v10
	v_cvt_pk_f32_fp8_e32 v[226:227], v14
	v_cvt_pk_f32_fp8_sdwa v[220:221], v10 src0_sel:WORD_1
	v_cvt_pk_f32_fp8_sdwa v[228:229], v14 src0_sel:WORD_1
	v_cvt_pk_f32_fp8_e32 v[222:223], v11
	v_cvt_pk_f32_fp8_e32 v[230:231], v15
	v_cvt_pk_f32_fp8_sdwa v[224:225], v11 src0_sel:WORD_1
	v_cvt_pk_f32_fp8_sdwa v[232:233], v15 src0_sel:WORD_1
	v_pk_fma_f32 v[250:251], v[218:219], v[136:137], v[250:251]
	v_pk_fma_f32 v[252:253], v[226:227], v[136:137], v[252:253]
	v_pk_fma_f32 v[250:251], v[220:221], v[138:139], v[250:251]
	v_pk_fma_f32 v[252:253], v[228:229], v[138:139], v[252:253]
	v_pk_fma_f32 v[250:251], v[222:223], v[140:141], v[250:251]
	v_pk_fma_f32 v[252:253], v[230:231], v[140:141], v[252:253]
	v_pk_fma_f32 v[250:251], v[224:225], v[142:143], v[250:251]
	v_pk_fma_f32 v[252:253], v[232:233], v[142:143], v[252:253]
	v_add_f32_e32 v204, v250, v251
	v_add_f32_e32 v205, v252, v253
	v_cvt_pk_f32_fp8_e32 v[218:219], v16
	v_cvt_pk_f32_fp8_e32 v[226:227], v20
	v_cvt_pk_f32_fp8_sdwa v[220:221], v16 src0_sel:WORD_1
	v_cvt_pk_f32_fp8_sdwa v[228:229], v20 src0_sel:WORD_1
	v_cvt_pk_f32_fp8_e32 v[222:223], v17
	v_cvt_pk_f32_fp8_e32 v[230:231], v21
	v_cvt_pk_f32_fp8_sdwa v[224:225], v17 src0_sel:WORD_1
	v_cvt_pk_f32_fp8_sdwa v[232:233], v21 src0_sel:WORD_1
	v_pk_mul_f32 v[250:251], v[218:219], v[128:129]
	v_pk_mul_f32 v[252:253], v[226:227], v[128:129]
	v_pk_fma_f32 v[250:251], v[220:221], v[130:131], v[250:251]
	v_pk_fma_f32 v[252:253], v[228:229], v[130:131], v[252:253]
	v_pk_fma_f32 v[250:251], v[222:223], v[132:133], v[250:251]
	v_pk_fma_f32 v[252:253], v[230:231], v[132:133], v[252:253]
	v_pk_fma_f32 v[250:251], v[224:225], v[134:135], v[250:251]
	v_pk_fma_f32 v[252:253], v[232:233], v[134:135], v[252:253]
	v_cvt_pk_f32_fp8_e32 v[218:219], v18
	v_cvt_pk_f32_fp8_e32 v[226:227], v22
	v_cvt_pk_f32_fp8_sdwa v[220:221], v18 src0_sel:WORD_1
	v_cvt_pk_f32_fp8_sdwa v[228:229], v22 src0_sel:WORD_1
	v_cvt_pk_f32_fp8_e32 v[222:223], v19
	v_cvt_pk_f32_fp8_e32 v[230:231], v23
	v_cvt_pk_f32_fp8_sdwa v[224:225], v19 src0_sel:WORD_1
	v_cvt_pk_f32_fp8_sdwa v[232:233], v23 src0_sel:WORD_1
	v_pk_fma_f32 v[250:251], v[218:219], v[136:137], v[250:251]
	v_pk_fma_f32 v[252:253], v[226:227], v[136:137], v[252:253]
	v_pk_fma_f32 v[250:251], v[220:221], v[138:139], v[250:251]
	v_pk_fma_f32 v[252:253], v[228:229], v[138:139], v[252:253]
	v_pk_fma_f32 v[250:251], v[222:223], v[140:141], v[250:251]
	v_pk_fma_f32 v[252:253], v[230:231], v[140:141], v[252:253]
	v_pk_fma_f32 v[250:251], v[224:225], v[142:143], v[250:251]
	v_pk_fma_f32 v[252:253], v[232:233], v[142:143], v[252:253]
	v_add_f32_e32 v206, v250, v251
	v_add_f32_e32 v207, v252, v253
	v_cvt_pk_f32_fp8_e32 v[218:219], v24
	v_cvt_pk_f32_fp8_e32 v[226:227], v28
	v_cvt_pk_f32_fp8_sdwa v[220:221], v24 src0_sel:WORD_1
	v_cvt_pk_f32_fp8_sdwa v[228:229], v28 src0_sel:WORD_1
	v_cvt_pk_f32_fp8_e32 v[222:223], v25
	v_cvt_pk_f32_fp8_e32 v[230:231], v29
	v_cvt_pk_f32_fp8_sdwa v[224:225], v25 src0_sel:WORD_1
	v_cvt_pk_f32_fp8_sdwa v[232:233], v29 src0_sel:WORD_1
	v_pk_mul_f32 v[250:251], v[218:219], v[128:129]
	v_pk_mul_f32 v[252:253], v[226:227], v[128:129]
	v_pk_fma_f32 v[250:251], v[220:221], v[130:131], v[250:251]
	v_pk_fma_f32 v[252:253], v[228:229], v[130:131], v[252:253]
	v_pk_fma_f32 v[250:251], v[222:223], v[132:133], v[250:251]
	v_pk_fma_f32 v[252:253], v[230:231], v[132:133], v[252:253]
	v_pk_fma_f32 v[250:251], v[224:225], v[134:135], v[250:251]
	v_pk_fma_f32 v[252:253], v[232:233], v[134:135], v[252:253]
	v_cvt_pk_f32_fp8_e32 v[218:219], v26
	v_cvt_pk_f32_fp8_e32 v[226:227], v30
	v_cvt_pk_f32_fp8_sdwa v[220:221], v26 src0_sel:WORD_1
	v_cvt_pk_f32_fp8_sdwa v[228:229], v30 src0_sel:WORD_1
	v_cvt_pk_f32_fp8_e32 v[222:223], v27
	v_cvt_pk_f32_fp8_e32 v[230:231], v31
	v_cvt_pk_f32_fp8_sdwa v[224:225], v27 src0_sel:WORD_1
	v_cvt_pk_f32_fp8_sdwa v[232:233], v31 src0_sel:WORD_1
	v_pk_fma_f32 v[250:251], v[218:219], v[136:137], v[250:251]
	v_pk_fma_f32 v[252:253], v[226:227], v[136:137], v[252:253]
	v_pk_fma_f32 v[250:251], v[220:221], v[138:139], v[250:251]
	v_pk_fma_f32 v[252:253], v[228:229], v[138:139], v[252:253]
	v_pk_fma_f32 v[250:251], v[222:223], v[140:141], v[250:251]
	v_pk_fma_f32 v[252:253], v[230:231], v[140:141], v[252:253]
	v_pk_fma_f32 v[250:251], v[224:225], v[142:143], v[250:251]
	v_pk_fma_f32 v[252:253], v[232:233], v[142:143], v[252:253]
	v_add_f32_e32 v208, v250, v251
	v_add_f32_e32 v209, v252, v253
	v_cvt_pk_f32_fp8_e32 v[218:219], v32
	v_cvt_pk_f32_fp8_e32 v[226:227], v36
	v_cvt_pk_f32_fp8_sdwa v[220:221], v32 src0_sel:WORD_1
	v_cvt_pk_f32_fp8_sdwa v[228:229], v36 src0_sel:WORD_1
	v_cvt_pk_f32_fp8_e32 v[222:223], v33
	v_cvt_pk_f32_fp8_e32 v[230:231], v37
	v_cvt_pk_f32_fp8_sdwa v[224:225], v33 src0_sel:WORD_1
	v_cvt_pk_f32_fp8_sdwa v[232:233], v37 src0_sel:WORD_1
	v_pk_mul_f32 v[250:251], v[218:219], v[128:129]
	v_pk_mul_f32 v[252:253], v[226:227], v[128:129]
	v_pk_fma_f32 v[250:251], v[220:221], v[130:131], v[250:251]
	v_pk_fma_f32 v[252:253], v[228:229], v[130:131], v[252:253]
	v_pk_fma_f32 v[250:251], v[222:223], v[132:133], v[250:251]
	v_pk_fma_f32 v[252:253], v[230:231], v[132:133], v[252:253]
	v_pk_fma_f32 v[250:251], v[224:225], v[134:135], v[250:251]
	v_pk_fma_f32 v[252:253], v[232:233], v[134:135], v[252:253]
	v_cvt_pk_f32_fp8_e32 v[218:219], v34
	v_cvt_pk_f32_fp8_e32 v[226:227], v38
	v_cvt_pk_f32_fp8_sdwa v[220:221], v34 src0_sel:WORD_1
	v_cvt_pk_f32_fp8_sdwa v[228:229], v38 src0_sel:WORD_1
	v_cvt_pk_f32_fp8_e32 v[222:223], v35
	v_cvt_pk_f32_fp8_e32 v[230:231], v39
	v_cvt_pk_f32_fp8_sdwa v[224:225], v35 src0_sel:WORD_1
	v_cvt_pk_f32_fp8_sdwa v[232:233], v39 src0_sel:WORD_1
	v_pk_fma_f32 v[250:251], v[218:219], v[136:137], v[250:251]
	v_pk_fma_f32 v[252:253], v[226:227], v[136:137], v[252:253]
	v_pk_fma_f32 v[250:251], v[220:221], v[138:139], v[250:251]
	v_pk_fma_f32 v[252:253], v[228:229], v[138:139], v[252:253]
	v_pk_fma_f32 v[250:251], v[222:223], v[140:141], v[250:251]
	v_pk_fma_f32 v[252:253], v[230:231], v[140:141], v[252:253]
	v_pk_fma_f32 v[250:251], v[224:225], v[142:143], v[250:251]
	v_pk_fma_f32 v[252:253], v[232:233], v[142:143], v[252:253]
	v_add_f32_e32 v210, v250, v251
	v_add_f32_e32 v211, v252, v253
	v_cvt_pk_f32_fp8_e32 v[218:219], v40
	v_cvt_pk_f32_fp8_e32 v[226:227], v44
	v_cvt_pk_f32_fp8_sdwa v[220:221], v40 src0_sel:WORD_1
	v_cvt_pk_f32_fp8_sdwa v[228:229], v44 src0_sel:WORD_1
	v_cvt_pk_f32_fp8_e32 v[222:223], v41
	v_cvt_pk_f32_fp8_e32 v[230:231], v45
	v_cvt_pk_f32_fp8_sdwa v[224:225], v41 src0_sel:WORD_1
	v_cvt_pk_f32_fp8_sdwa v[232:233], v45 src0_sel:WORD_1
	v_pk_mul_f32 v[250:251], v[218:219], v[128:129]
	v_pk_mul_f32 v[252:253], v[226:227], v[128:129]
	v_pk_fma_f32 v[250:251], v[220:221], v[130:131], v[250:251]
	v_pk_fma_f32 v[252:253], v[228:229], v[130:131], v[252:253]
	v_pk_fma_f32 v[250:251], v[222:223], v[132:133], v[250:251]
	v_pk_fma_f32 v[252:253], v[230:231], v[132:133], v[252:253]
	v_pk_fma_f32 v[250:251], v[224:225], v[134:135], v[250:251]
	v_pk_fma_f32 v[252:253], v[232:233], v[134:135], v[252:253]
	v_cvt_pk_f32_fp8_e32 v[218:219], v42
	v_cvt_pk_f32_fp8_e32 v[226:227], v46
	v_cvt_pk_f32_fp8_sdwa v[220:221], v42 src0_sel:WORD_1
	v_cvt_pk_f32_fp8_sdwa v[228:229], v46 src0_sel:WORD_1
	v_cvt_pk_f32_fp8_e32 v[222:223], v43
	v_cvt_pk_f32_fp8_e32 v[230:231], v47
	v_cvt_pk_f32_fp8_sdwa v[224:225], v43 src0_sel:WORD_1
	v_cvt_pk_f32_fp8_sdwa v[232:233], v47 src0_sel:WORD_1
	v_pk_fma_f32 v[250:251], v[218:219], v[136:137], v[250:251]
	v_pk_fma_f32 v[252:253], v[226:227], v[136:137], v[252:253]
	v_pk_fma_f32 v[250:251], v[220:221], v[138:139], v[250:251]
	v_pk_fma_f32 v[252:253], v[228:229], v[138:139], v[252:253]
	v_pk_fma_f32 v[250:251], v[222:223], v[140:141], v[250:251]
	v_pk_fma_f32 v[252:253], v[230:231], v[140:141], v[252:253]
	v_pk_fma_f32 v[250:251], v[224:225], v[142:143], v[250:251]
	v_pk_fma_f32 v[252:253], v[232:233], v[142:143], v[252:253]
	v_add_f32_e32 v212, v250, v251
	v_add_f32_e32 v213, v252, v253
	v_cvt_pk_f32_fp8_e32 v[218:219], v48
	v_cvt_pk_f32_fp8_e32 v[226:227], v52
	v_cvt_pk_f32_fp8_sdwa v[220:221], v48 src0_sel:WORD_1
	v_cvt_pk_f32_fp8_sdwa v[228:229], v52 src0_sel:WORD_1
	v_cvt_pk_f32_fp8_e32 v[222:223], v49
	v_cvt_pk_f32_fp8_e32 v[230:231], v53
	v_cvt_pk_f32_fp8_sdwa v[224:225], v49 src0_sel:WORD_1
	v_cvt_pk_f32_fp8_sdwa v[232:233], v53 src0_sel:WORD_1
	v_pk_mul_f32 v[250:251], v[218:219], v[128:129]
	v_pk_mul_f32 v[252:253], v[226:227], v[128:129]
	v_pk_fma_f32 v[250:251], v[220:221], v[130:131], v[250:251]
	v_pk_fma_f32 v[252:253], v[228:229], v[130:131], v[252:253]
	v_pk_fma_f32 v[250:251], v[222:223], v[132:133], v[250:251]
	v_pk_fma_f32 v[252:253], v[230:231], v[132:133], v[252:253]
	v_pk_fma_f32 v[250:251], v[224:225], v[134:135], v[250:251]
	v_pk_fma_f32 v[252:253], v[232:233], v[134:135], v[252:253]
	v_cvt_pk_f32_fp8_e32 v[218:219], v50
	v_cvt_pk_f32_fp8_e32 v[226:227], v54
	v_cvt_pk_f32_fp8_sdwa v[220:221], v50 src0_sel:WORD_1
	v_cvt_pk_f32_fp8_sdwa v[228:229], v54 src0_sel:WORD_1
	v_cvt_pk_f32_fp8_e32 v[222:223], v51
	v_cvt_pk_f32_fp8_e32 v[230:231], v55
	v_cvt_pk_f32_fp8_sdwa v[224:225], v51 src0_sel:WORD_1
	v_cvt_pk_f32_fp8_sdwa v[232:233], v55 src0_sel:WORD_1
	v_pk_fma_f32 v[250:251], v[218:219], v[136:137], v[250:251]
	v_pk_fma_f32 v[252:253], v[226:227], v[136:137], v[252:253]
	v_pk_fma_f32 v[250:251], v[220:221], v[138:139], v[250:251]
	v_pk_fma_f32 v[252:253], v[228:229], v[138:139], v[252:253]
	v_pk_fma_f32 v[250:251], v[222:223], v[140:141], v[250:251]
	v_pk_fma_f32 v[252:253], v[230:231], v[140:141], v[252:253]
	v_pk_fma_f32 v[250:251], v[224:225], v[142:143], v[250:251]
	v_pk_fma_f32 v[252:253], v[232:233], v[142:143], v[252:253]
	v_add_f32_e32 v214, v250, v251
	v_add_f32_e32 v215, v252, v253
	v_cvt_pk_f32_fp8_e32 v[218:219], v56
	v_cvt_pk_f32_fp8_e32 v[226:227], v60
	v_cvt_pk_f32_fp8_sdwa v[220:221], v56 src0_sel:WORD_1
	v_cvt_pk_f32_fp8_sdwa v[228:229], v60 src0_sel:WORD_1
	v_cvt_pk_f32_fp8_e32 v[222:223], v57
	v_cvt_pk_f32_fp8_e32 v[230:231], v61
	v_cvt_pk_f32_fp8_sdwa v[224:225], v57 src0_sel:WORD_1
	v_cvt_pk_f32_fp8_sdwa v[232:233], v61 src0_sel:WORD_1
	v_pk_mul_f32 v[250:251], v[218:219], v[128:129]
	v_pk_mul_f32 v[252:253], v[226:227], v[128:129]
	v_pk_fma_f32 v[250:251], v[220:221], v[130:131], v[250:251]
	v_pk_fma_f32 v[252:253], v[228:229], v[130:131], v[252:253]
	v_pk_fma_f32 v[250:251], v[222:223], v[132:133], v[250:251]
	v_pk_fma_f32 v[252:253], v[230:231], v[132:133], v[252:253]
	v_pk_fma_f32 v[250:251], v[224:225], v[134:135], v[250:251]
	v_pk_fma_f32 v[252:253], v[232:233], v[134:135], v[252:253]
	v_cvt_pk_f32_fp8_e32 v[218:219], v58
	v_cvt_pk_f32_fp8_e32 v[226:227], v62
	v_cvt_pk_f32_fp8_sdwa v[220:221], v58 src0_sel:WORD_1
	v_cvt_pk_f32_fp8_sdwa v[228:229], v62 src0_sel:WORD_1
	v_cvt_pk_f32_fp8_e32 v[222:223], v59
	v_cvt_pk_f32_fp8_e32 v[230:231], v63
	v_cvt_pk_f32_fp8_sdwa v[224:225], v59 src0_sel:WORD_1
	v_cvt_pk_f32_fp8_sdwa v[232:233], v63 src0_sel:WORD_1
	v_pk_fma_f32 v[250:251], v[218:219], v[136:137], v[250:251]
	v_pk_fma_f32 v[252:253], v[226:227], v[136:137], v[252:253]
	v_pk_fma_f32 v[250:251], v[220:221], v[138:139], v[250:251]
	v_pk_fma_f32 v[252:253], v[228:229], v[138:139], v[252:253]
	v_pk_fma_f32 v[250:251], v[222:223], v[140:141], v[250:251]
	v_pk_fma_f32 v[252:253], v[230:231], v[140:141], v[252:253]
	v_pk_fma_f32 v[250:251], v[224:225], v[142:143], v[250:251]
	v_pk_fma_f32 v[252:253], v[232:233], v[142:143], v[252:253]
	v_add_f32_e32 v216, v250, v251
	v_add_f32_e32 v217, v252, v253
	s_lshl_b32 s34, s20, 9
	s_add_u32 s32, s12, s34
	s_addc_u32 s33, s13, 0
	s_nop 1
	v_add_f32_dpp v218, v202, v202 row_half_mirror row_mask:0xf bank_mask:0x5
	v_add_f32_dpp v219, v203, v203 row_half_mirror row_mask:0xf bank_mask:0x5
	v_add_f32_dpp v220, v204, v204 row_half_mirror row_mask:0xf bank_mask:0x5
	v_add_f32_dpp v221, v205, v205 row_half_mirror row_mask:0xf bank_mask:0x5
	v_add_f32_dpp v222, v206, v206 row_half_mirror row_mask:0xf bank_mask:0x5
	v_add_f32_dpp v223, v207, v207 row_half_mirror row_mask:0xf bank_mask:0x5
	v_add_f32_dpp v224, v208, v208 row_half_mirror row_mask:0xf bank_mask:0x5
	v_add_f32_dpp v225, v209, v209 row_half_mirror row_mask:0xf bank_mask:0x5
	v_add_f32_dpp v218, v210, v210 row_half_mirror row_mask:0xf bank_mask:0xa
	v_add_f32_dpp v219, v211, v211 row_half_mirror row_mask:0xf bank_mask:0xa
	v_add_f32_dpp v220, v212, v212 row_half_mirror row_mask:0xf bank_mask:0xa
	v_add_f32_dpp v221, v213, v213 row_half_mirror row_mask:0xf bank_mask:0xa
	v_add_f32_dpp v222, v214, v214 row_half_mirror row_mask:0xf bank_mask:0xa
	v_add_f32_dpp v223, v215, v215 row_half_mirror row_mask:0xf bank_mask:0xa
	v_add_f32_dpp v224, v216, v216 row_half_mirror row_mask:0xf bank_mask:0xa
	v_add_f32_dpp v225, v217, v217 row_half_mirror row_mask:0xf bank_mask:0xa
	v_cndmask_b32_e64 v226, v218, v222, s[26:27]
	v_cndmask_b32_e64 v227, v219, v223, s[26:27]
	v_cndmask_b32_e64 v228, v220, v224, s[26:27]
	v_cndmask_b32_e64 v229, v221, v225, s[26:27]
	v_cndmask_b32_e64 v230, v222, v218, s[26:27]
	v_cndmask_b32_e64 v231, v223, v219, s[26:27]
	v_cndmask_b32_e64 v232, v224, v220, s[26:27]
	v_cndmask_b32_e64 v233, v225, v221, s[26:27]
	s_nop 0
	v_add_f32_dpp v250, v230, v226 quad_perm:[2,3,0,1] row_mask:0xf bank_mask:0xf
	v_add_f32_dpp v251, v231, v227 quad_perm:[2,3,0,1] row_mask:0xf bank_mask:0xf
	v_add_f32_dpp v252, v232, v228 quad_perm:[2,3,0,1] row_mask:0xf bank_mask:0xf
	v_add_f32_dpp v253, v233, v229 quad_perm:[2,3,0,1] row_mask:0xf bank_mask:0xf
	v_cndmask_b32_e64 v226, v250, v252, s[28:29]
	v_cndmask_b32_e64 v227, v251, v253, s[28:29]
	v_cndmask_b32_e64 v230, v252, v250, s[28:29]
	v_cndmask_b32_e64 v231, v253, v251, s[28:29]
	s_nop 1
	v_add_f32_dpp v218, v230, v226 quad_perm:[1,0,3,2] row_mask:0xf bank_mask:0xf
	v_add_f32_dpp v219, v231, v227 quad_perm:[1,0,3,2] row_mask:0xf bank_mask:0xf
	global_store_dwordx2 v180, v[218:219], s[32:33]
	s_add_u32 s20, s20, s21
	s_cmp_lt_u32 s20, 0x4000
	s_cbranch_scc0 .Lgd_done_L0
	s_add_u32 s36, s20, s21
	s_add_u32 s37, s36, s21
	s_add_u32 s37, s37, s21
	s_min_u32 s36, s36, 0x3fff
	s_min_u32 s37, s37, 0x3fff
	s_waitcnt vmcnt(25)
	v_lshl_or_b32 v186, v186, 7, v176
	v_lshl_or_b32 v187, v187, 7, v176
	v_lshl_or_b32 v188, v188, 7, v176
	v_lshl_or_b32 v189, v189, 7, v176
	v_lshl_or_b32 v190, v190, 7, v176
	v_lshl_or_b32 v191, v191, 7, v176
	v_lshl_or_b32 v192, v192, 7, v176
	v_lshl_or_b32 v193, v193, 7, v176
	v_lshl_or_b32 v194, v194, 7, v176
	v_lshl_or_b32 v195, v195, 7, v176
	v_lshl_or_b32 v196, v196, 7, v176
	v_lshl_or_b32 v197, v197, 7, v176
	v_lshl_or_b32 v198, v198, 7, v176
	v_lshl_or_b32 v199, v199, 7, v176
	v_lshl_or_b32 v200, v200, 7, v176
	v_lshl_or_b32 v201, v201, 7, v176
	s_lshl_b32 s34, s36, 12
	s_add_u32 s24, s4, s34
	s_addc_u32 s25, s5, 0
	global_load_dwordx4 v[128:131], v177, s[24:25] offset:0
	global_load_dwordx4 v[132:135], v177, s[24:25] offset:16
	global_load_dwordx4 v[136:139], v177, s[24:25] offset:32
	global_load_dwordx4 v[140:143], v177, s[24:25] offset:48
	global_load_dwordx4 v[0:3], v186, s[2:3]
	global_load_dwordx4 v[4:7], v187, s[2:3]
	global_load_dwordx4 v[8:11], v188, s[2:3]
	global_load_dwordx4 v[12:15], v189, s[2:3]
	global_load_dwordx4 v[16:19], v190, s[2:3]
	global_load_dwordx4 v[20:23], v191, s[2:3]
	global_load_dwordx4 v[24:27], v192, s[2:3]
	global_load_dwordx4 v[28:31], v193, s[2:3]
	global_load_dwordx4 v[32:35], v194, s[2:3]
	global_load_dwordx4 v[36:39], v195, s[2:3]
	global_load_dwordx4 v[40:43], v196, s[2:3]
	global_load_dwordx4 v[44:47], v197, s[2:3]
	global_load_dwordx4 v[48:51], v198, s[2:3]
	global_load_dwordx4 v[52:55], v199, s[2:3]
	global_load_dwordx4 v[56:59], v200, s[2:3]
	global_load_dwordx4 v[60:63], v201, s[2:3]
	s_lshl_b32 s34, s37, 9
	s_add_u32 s22, s6, s34
	s_addc_u32 s23, s7, 0
	global_load_dwordx4 v[160:163], v181, s[22:23] offset:0
	global_load_dwordx4 v[164:167], v181, s[22:23] offset:16
	global_load_dwordx4 v[168:171], v181, s[22:23] offset:32
	global_load_dwordx4 v[172:175], v181, s[22:23] offset:48
	s_waitcnt vmcnt(29)
	v_cvt_pk_f32_fp8_e32 v[218:219], v64
	v_cvt_pk_f32_fp8_e32 v[226:227], v68
	v_cvt_pk_f32_fp8_sdwa v[220:221], v64 src0_sel:WORD_1
	v_cvt_pk_f32_fp8_sdwa v[228:229], v68 src0_sel:WORD_1
	v_cvt_pk_f32_fp8_e32 v[222:223], v65
	v_cvt_pk_f32_fp8_e32 v[230:231], v69
	v_cvt_pk_f32_fp8_sdwa v[224:225], v65 src0_sel:WORD_1
	v_cvt_pk_f32_fp8_sdwa v[232:233], v69 src0_sel:WORD_1
	v_pk_mul_f32 v[250:251], v[218:219], v[144:145]
	v_pk_mul_f32 v[252:253], v[226:227], v[144:145]
	v_pk_fma_f32 v[250:251], v[220:221], v[146:147], v[250:251]
	v_pk_fma_f32 v[252:253], v[228:229], v[146:147], v[252:253]
	v_pk_fma_f32 v[250:251], v[222:223], v[148:149], v[250:251]
	v_pk_fma_f32 v[252:253], v[230:231], v[148:149], v[252:253]
	v_pk_fma_f32 v[250:251], v[224:225], v[150:151], v[250:251]
	v_pk_fma_f32 v[252:253], v[232:233], v[150:151], v[252:253]
	v_cvt_pk_f32_fp8_e32 v[218:219], v66
	v_cvt_pk_f32_fp8_e32 v[226:227], v70
	v_cvt_pk_f32_fp8_sdwa v[220:221], v66 src0_sel:WORD_1
	v_cvt_pk_f32_fp8_sdwa v[228:229], v70 src0_sel:WORD_1
	v_cvt_pk_f32_fp8_e32 v[222:223], v67
	v_cvt_pk_f32_fp8_e32 v[230:231], v71
	v_cvt_pk_f32_fp8_sdwa v[224:225], v67 src0_sel:WORD_1
	v_cvt_pk_f32_fp8_sdwa v[232:233], v71 src0_sel:WORD_1
	v_pk_fma_f32 v[250:251], v[218:219], v[152:153], v[250:251]
	v_pk_fma_f32 v[252:253], v[226:227], v[152:153], v[252:253]
	v_pk_fma_f32 v[250:251], v[220:221], v[154:155], v[250:251]
	v_pk_fma_f32 v[252:253], v[228:229], v[154:155], v[252:253]
	v_pk_fma_f32 v[250:251], v[222:223], v[156:157], v[250:251]
	v_pk_fma_f32 v[252:253], v[230:231], v[156:157], v[252:253]
	v_pk_fma_f32 v[250:251], v[224:225], v[158:159], v[250:251]
	v_pk_fma_f32 v[252:253], v[232:233], v[158:159], v[252:253]
	v_add_f32_e32 v202, v250, v251
	v_add_f32_e32 v203, v252, v253
	v_cvt_pk_f32_fp8_e32 v[218:219], v72
	v_cvt_pk_f32_fp8_e32 v[226:227], v76
	v_cvt_pk_f32_fp8_sdwa v[220:221], v72 src0_sel:WORD_1
	v_cvt_pk_f32_fp8_sdwa v[228:229], v76 src0_sel:WORD_1
	v_cvt_pk_f32_fp8_e32 v[222:223], v73
	v_cvt_pk_f32_fp8_e32 v[230:231], v77
	v_cvt_pk_f32_fp8_sdwa v[224:225], v73 src0_sel:WORD_1
	v_cvt_pk_f32_fp8_sdwa v[232:233], v77 src0_sel:WORD_1
	v_pk_mul_f32 v[250:251], v[218:219], v[144:145]
	v_pk_mul_f32 v[252:253], v[226:227], v[144:145]
	v_pk_fma_f32 v[250:251], v[220:221], v[146:147], v[250:251]
	v_pk_fma_f32 v[252:253], v[228:229], v[146:147], v[252:253]
	v_pk_fma_f32 v[250:251], v[222:223], v[148:149], v[250:251]
	v_pk_fma_f32 v[252:253], v[230:231], v[148:149], v[252:253]
	v_pk_fma_f32 v[250:251], v[224:225], v[150:151], v[250:251]
	v_pk_fma_f32 v[252:253], v[232:233], v[150:151], v[252:253]
	v_cvt_pk_f32_fp8_e32 v[218:219], v74
	v_cvt_pk_f32_fp8_e32 v[226:227], v78
	v_cvt_pk_f32_fp8_sdwa v[220:221], v74 src0_sel:WORD_1
	v_cvt_pk_f32_fp8_sdwa v[228:229], v78 src0_sel:WORD_1
	v_cvt_pk_f32_fp8_e32 v[222:223], v75
	v_cvt_pk_f32_fp8_e32 v[230:231], v79
	v_cvt_pk_f32_fp8_sdwa v[224:225], v75 src0_sel:WORD_1
	v_cvt_pk_f32_fp8_sdwa v[232:233], v79 src0_sel:WORD_1
	v_pk_fma_f32 v[250:251], v[218:219], v[152:153], v[250:251]
	v_pk_fma_f32 v[252:253], v[226:227], v[152:153], v[252:253]
	v_pk_fma_f32 v[250:251], v[220:221], v[154:155], v[250:251]
	v_pk_fma_f32 v[252:253], v[228:229], v[154:155], v[252:253]
	v_pk_fma_f32 v[250:251], v[222:223], v[156:157], v[250:251]
	v_pk_fma_f32 v[252:253], v[230:231], v[156:157], v[252:253]
	v_pk_fma_f32 v[250:251], v[224:225], v[158:159], v[250:251]
	v_pk_fma_f32 v[252:253], v[232:233], v[158:159], v[252:253]
	v_add_f32_e32 v204, v250, v251
	v_add_f32_e32 v205, v252, v253
	v_cvt_pk_f32_fp8_e32 v[218:219], v80
	v_cvt_pk_f32_fp8_e32 v[226:227], v84
	v_cvt_pk_f32_fp8_sdwa v[220:221], v80 src0_sel:WORD_1
	v_cvt_pk_f32_fp8_sdwa v[228:229], v84 src0_sel:WORD_1
	v_cvt_pk_f32_fp8_e32 v[222:223], v81
	v_cvt_pk_f32_fp8_e32 v[230:231], v85
	v_cvt_pk_f32_fp8_sdwa v[224:225], v81 src0_sel:WORD_1
	v_cvt_pk_f32_fp8_sdwa v[232:233], v85 src0_sel:WORD_1
	v_pk_mul_f32 v[250:251], v[218:219], v[144:145]
	v_pk_mul_f32 v[252:253], v[226:227], v[144:145]
	v_pk_fma_f32 v[250:251], v[220:221], v[146:147], v[250:251]
	v_pk_fma_f32 v[252:253], v[228:229], v[146:147], v[252:253]
	v_pk_fma_f32 v[250:251], v[222:223], v[148:149], v[250:251]
	v_pk_fma_f32 v[252:253], v[230:231], v[148:149], v[252:253]
	v_pk_fma_f32 v[250:251], v[224:225], v[150:151], v[250:251]
	v_pk_fma_f32 v[252:253], v[232:233], v[150:151], v[252:253]
	v_cvt_pk_f32_fp8_e32 v[218:219], v82
	v_cvt_pk_f32_fp8_e32 v[226:227], v86
	v_cvt_pk_f32_fp8_sdwa v[220:221], v82 src0_sel:WORD_1
	v_cvt_pk_f32_fp8_sdwa v[228:229], v86 src0_sel:WORD_1
	v_cvt_pk_f32_fp8_e32 v[222:223], v83
	v_cvt_pk_f32_fp8_e32 v[230:231], v87
	v_cvt_pk_f32_fp8_sdwa v[224:225], v83 src0_sel:WORD_1
	v_cvt_pk_f32_fp8_sdwa v[232:233], v87 src0_sel:WORD_1
	v_pk_fma_f32 v[250:251], v[218:219], v[152:153], v[250:251]
	v_pk_fma_f32 v[252:253], v[226:227], v[152:153], v[252:253]
	v_pk_fma_f32 v[250:251], v[220:221], v[154:155], v[250:251]
	v_pk_fma_f32 v[252:253], v[228:229], v[154:155], v[252:253]
	v_pk_fma_f32 v[250:251], v[222:223], v[156:157], v[250:251]
	v_pk_fma_f32 v[252:253], v[230:231], v[156:157], v[252:253]
	v_pk_fma_f32 v[250:251], v[224:225], v[158:159], v[250:251]
	v_pk_fma_f32 v[252:253], v[232:233], v[158:159], v[252:253]
	v_add_f32_e32 v206, v250, v251
	v_add_f32_e32 v207, v252, v253
	v_cvt_pk_f32_fp8_e32 v[218:219], v88
	v_cvt_pk_f32_fp8_e32 v[226:227], v92
	v_cvt_pk_f32_fp8_sdwa v[220:221], v88 src0_sel:WORD_1
	v_cvt_pk_f32_fp8_sdwa v[228:229], v92 src0_sel:WORD_1
	v_cvt_pk_f32_fp8_e32 v[222:223], v89
	v_cvt_pk_f32_fp8_e32 v[230:231], v93
	v_cvt_pk_f32_fp8_sdwa v[224:225], v89 src0_sel:WORD_1
	v_cvt_pk_f32_fp8_sdwa v[232:233], v93 src0_sel:WORD_1
	v_pk_mul_f32 v[250:251], v[218:219], v[144:145]
	v_pk_mul_f32 v[252:253], v[226:227], v[144:145]
	v_pk_fma_f32 v[250:251], v[220:221], v[146:147], v[250:251]
	v_pk_fma_f32 v[252:253], v[228:229], v[146:147], v[252:253]
	v_pk_fma_f32 v[250:251], v[222:223], v[148:149], v[250:251]
	v_pk_fma_f32 v[252:253], v[230:231], v[148:149], v[252:253]
	v_pk_fma_f32 v[250:251], v[224:225], v[150:151], v[250:251]
	v_pk_fma_f32 v[252:253], v[232:233], v[150:151], v[252:253]
	v_cvt_pk_f32_fp8_e32 v[218:219], v90
	v_cvt_pk_f32_fp8_e32 v[226:227], v94
	v_cvt_pk_f32_fp8_sdwa v[220:221], v90 src0_sel:WORD_1
	v_cvt_pk_f32_fp8_sdwa v[228:229], v94 src0_sel:WORD_1
	v_cvt_pk_f32_fp8_e32 v[222:223], v91
	v_cvt_pk_f32_fp8_e32 v[230:231], v95
	v_cvt_pk_f32_fp8_sdwa v[224:225], v91 src0_sel:WORD_1
	v_cvt_pk_f32_fp8_sdwa v[232:233], v95 src0_sel:WORD_1
	v_pk_fma_f32 v[250:251], v[218:219], v[152:153], v[250:251]
	v_pk_fma_f32 v[252:253], v[226:227], v[152:153], v[252:253]
	v_pk_fma_f32 v[250:251], v[220:221], v[154:155], v[250:251]
	v_pk_fma_f32 v[252:253], v[228:229], v[154:155], v[252:253]
	v_pk_fma_f32 v[250:251], v[222:223], v[156:157], v[250:251]
	v_pk_fma_f32 v[252:253], v[230:231], v[156:157], v[252:253]
	v_pk_fma_f32 v[250:251], v[224:225], v[158:159], v[250:251]
	v_pk_fma_f32 v[252:253], v[232:233], v[158:159], v[252:253]
	v_add_f32_e32 v208, v250, v251
	v_add_f32_e32 v209, v252, v253
	v_cvt_pk_f32_fp8_e32 v[218:219], v96
	v_cvt_pk_f32_fp8_e32 v[226:227], v100
	v_cvt_pk_f32_fp8_sdwa v[220:221], v96 src0_sel:WORD_1
	v_cvt_pk_f32_fp8_sdwa v[228:229], v100 src0_sel:WORD_1
	v_cvt_pk_f32_fp8_e32 v[222:223], v97
	v_cvt_pk_f32_fp8_e32 v[230:231], v101
	v_cvt_pk_f32_fp8_sdwa v[224:225], v97 src0_sel:WORD_1
	v_cvt_pk_f32_fp8_sdwa v[232:233], v101 src0_sel:WORD_1
	v_pk_mul_f32 v[250:251], v[218:219], v[144:145]
	v_pk_mul_f32 v[252:253], v[226:227], v[144:145]
	v_pk_fma_f32 v[250:251], v[220:221], v[146:147], v[250:251]
	v_pk_fma_f32 v[252:253], v[228:229], v[146:147], v[252:253]
	v_pk_fma_f32 v[250:251], v[222:223], v[148:149], v[250:251]
	v_pk_fma_f32 v[252:253], v[230:231], v[148:149], v[252:253]
	v_pk_fma_f32 v[250:251], v[224:225], v[150:151], v[250:251]
	v_pk_fma_f32 v[252:253], v[232:233], v[150:151], v[252:253]
	v_cvt_pk_f32_fp8_e32 v[218:219], v98
	v_cvt_pk_f32_fp8_e32 v[226:227], v102
	v_cvt_pk_f32_fp8_sdwa v[220:221], v98 src0_sel:WORD_1
	v_cvt_pk_f32_fp8_sdwa v[228:229], v102 src0_sel:WORD_1
	v_cvt_pk_f32_fp8_e32 v[222:223], v99
	v_cvt_pk_f32_fp8_e32 v[230:231], v103
	v_cvt_pk_f32_fp8_sdwa v[224:225], v99 src0_sel:WORD_1
	v_cvt_pk_f32_fp8_sdwa v[232:233], v103 src0_sel:WORD_1
	v_pk_fma_f32 v[250:251], v[218:219], v[152:153], v[250:251]
	v_pk_fma_f32 v[252:253], v[226:227], v[152:153], v[252:253]
	v_pk_fma_f32 v[250:251], v[220:221], v[154:155], v[250:251]
	v_pk_fma_f32 v[252:253], v[228:229], v[154:155], v[252:253]
	v_pk_fma_f32 v[250:251], v[222:223], v[156:157], v[250:251]
	v_pk_fma_f32 v[252:253], v[230:231], v[156:157], v[252:253]
	v_pk_fma_f32 v[250:251], v[224:225], v[158:159], v[250:251]
	v_pk_fma_f32 v[252:253], v[232:233], v[158:159], v[252:253]
	v_add_f32_e32 v210, v250, v251
	v_add_f32_e32 v211, v252, v253
	v_cvt_pk_f32_fp8_e32 v[218:219], v104
	v_cvt_pk_f32_fp8_e32 v[226:227], v108
	v_cvt_pk_f32_fp8_sdwa v[220:221], v104 src0_sel:WORD_1
	v_cvt_pk_f32_fp8_sdwa v[228:229], v108 src0_sel:WORD_1
	v_cvt_pk_f32_fp8_e32 v[222:223], v105
	v_cvt_pk_f32_fp8_e32 v[230:231], v109
	v_cvt_pk_f32_fp8_sdwa v[224:225], v105 src0_sel:WORD_1
	v_cvt_pk_f32_fp8_sdwa v[232:233], v109 src0_sel:WORD_1
	v_pk_mul_f32 v[250:251], v[218:219], v[144:145]
	v_pk_mul_f32 v[252:253], v[226:227], v[144:145]
	v_pk_fma_f32 v[250:251], v[220:221], v[146:147], v[250:251]
	v_pk_fma_f32 v[252:253], v[228:229], v[146:147], v[252:253]
	v_pk_fma_f32 v[250:251], v[222:223], v[148:149], v[250:251]
	v_pk_fma_f32 v[252:253], v[230:231], v[148:149], v[252:253]
	v_pk_fma_f32 v[250:251], v[224:225], v[150:151], v[250:251]
	v_pk_fma_f32 v[252:253], v[232:233], v[150:151], v[252:253]
	v_cvt_pk_f32_fp8_e32 v[218:219], v106
	v_cvt_pk_f32_fp8_e32 v[226:227], v110
	v_cvt_pk_f32_fp8_sdwa v[220:221], v106 src0_sel:WORD_1
	v_cvt_pk_f32_fp8_sdwa v[228:229], v110 src0_sel:WORD_1
	v_cvt_pk_f32_fp8_e32 v[222:223], v107
	v_cvt_pk_f32_fp8_e32 v[230:231], v111
	v_cvt_pk_f32_fp8_sdwa v[224:225], v107 src0_sel:WORD_1
	v_cvt_pk_f32_fp8_sdwa v[232:233], v111 src0_sel:WORD_1
	v_pk_fma_f32 v[250:251], v[218:219], v[152:153], v[250:251]
	v_pk_fma_f32 v[252:253], v[226:227], v[152:153], v[252:253]
	v_pk_fma_f32 v[250:251], v[220:221], v[154:155], v[250:251]
	v_pk_fma_f32 v[252:253], v[228:229], v[154:155], v[252:253]
	v_pk_fma_f32 v[250:251], v[222:223], v[156:157], v[250:251]
	v_pk_fma_f32 v[252:253], v[230:231], v[156:157], v[252:253]
	v_pk_fma_f32 v[250:251], v[224:225], v[158:159], v[250:251]
	v_pk_fma_f32 v[252:253], v[232:233], v[158:159], v[252:253]
	v_add_f32_e32 v212, v250, v251
	v_add_f32_e32 v213, v252, v253
	v_cvt_pk_f32_fp8_e32 v[218:219], v112
	v_cvt_pk_f32_fp8_e32 v[226:227], v116
	v_cvt_pk_f32_fp8_sdwa v[220:221], v112 src0_sel:WORD_1
	v_cvt_pk_f32_fp8_sdwa v[228:229], v116 src0_sel:WORD_1
	v_cvt_pk_f32_fp8_e32 v[222:223], v113
	v_cvt_pk_f32_fp8_e32 v[230:231], v117
	v_cvt_pk_f32_fp8_sdwa v[224:225], v113 src0_sel:WORD_1
	v_cvt_pk_f32_fp8_sdwa v[232:233], v117 src0_sel:WORD_1
	v_pk_mul_f32 v[250:251], v[218:219], v[144:145]
	v_pk_mul_f32 v[252:253], v[226:227], v[144:145]
	v_pk_fma_f32 v[250:251], v[220:221], v[146:147], v[250:251]
	v_pk_fma_f32 v[252:253], v[228:229], v[146:147], v[252:253]
	v_pk_fma_f32 v[250:251], v[222:223], v[148:149], v[250:251]
	v_pk_fma_f32 v[252:253], v[230:231], v[148:149], v[252:253]
	v_pk_fma_f32 v[250:251], v[224:225], v[150:151], v[250:251]
	v_pk_fma_f32 v[252:253], v[232:233], v[150:151], v[252:253]
	v_cvt_pk_f32_fp8_e32 v[218:219], v114
	v_cvt_pk_f32_fp8_e32 v[226:227], v118
	v_cvt_pk_f32_fp8_sdwa v[220:221], v114 src0_sel:WORD_1
	v_cvt_pk_f32_fp8_sdwa v[228:229], v118 src0_sel:WORD_1
	v_cvt_pk_f32_fp8_e32 v[222:223], v115
	v_cvt_pk_f32_fp8_e32 v[230:231], v119
	v_cvt_pk_f32_fp8_sdwa v[224:225], v115 src0_sel:WORD_1
	v_cvt_pk_f32_fp8_sdwa v[232:233], v119 src0_sel:WORD_1
	v_pk_fma_f32 v[250:251], v[218:219], v[152:153], v[250:251]
	v_pk_fma_f32 v[252:253], v[226:227], v[152:153], v[252:253]
	v_pk_fma_f32 v[250:251], v[220:221], v[154:155], v[250:251]
	v_pk_fma_f32 v[252:253], v[228:229], v[154:155], v[252:253]
	v_pk_fma_f32 v[250:251], v[222:223], v[156:157], v[250:251]
	v_pk_fma_f32 v[252:253], v[230:231], v[156:157], v[252:253]
	v_pk_fma_f32 v[250:251], v[224:225], v[158:159], v[250:251]
	v_pk_fma_f32 v[252:253], v[232:233], v[158:159], v[252:253]
	v_add_f32_e32 v214, v250, v251
	v_add_f32_e32 v215, v252, v253
	v_cvt_pk_f32_fp8_e32 v[218:219], v120
	v_cvt_pk_f32_fp8_e32 v[226:227], v124
	v_cvt_pk_f32_fp8_sdwa v[220:221], v120 src0_sel:WORD_1
	v_cvt_pk_f32_fp8_sdwa v[228:229], v124 src0_sel:WORD_1
	v_cvt_pk_f32_fp8_e32 v[222:223], v121
	v_cvt_pk_f32_fp8_e32 v[230:231], v125
	v_cvt_pk_f32_fp8_sdwa v[224:225], v121 src0_sel:WORD_1
	v_cvt_pk_f32_fp8_sdwa v[232:233], v125 src0_sel:WORD_1
	v_pk_mul_f32 v[250:251], v[218:219], v[144:145]
	v_pk_mul_f32 v[252:253], v[226:227], v[144:145]
	v_pk_fma_f32 v[250:251], v[220:221], v[146:147], v[250:251]
	v_pk_fma_f32 v[252:253], v[228:229], v[146:147], v[252:253]
	v_pk_fma_f32 v[250:251], v[222:223], v[148:149], v[250:251]
	v_pk_fma_f32 v[252:253], v[230:231], v[148:149], v[252:253]
	v_pk_fma_f32 v[250:251], v[224:225], v[150:151], v[250:251]
	v_pk_fma_f32 v[252:253], v[232:233], v[150:151], v[252:253]
	v_cvt_pk_f32_fp8_e32 v[218:219], v122
	v_cvt_pk_f32_fp8_e32 v[226:227], v126
	v_cvt_pk_f32_fp8_sdwa v[220:221], v122 src0_sel:WORD_1
	v_cvt_pk_f32_fp8_sdwa v[228:229], v126 src0_sel:WORD_1
	v_cvt_pk_f32_fp8_e32 v[222:223], v123
	v_cvt_pk_f32_fp8_e32 v[230:231], v127
	v_cvt_pk_f32_fp8_sdwa v[224:225], v123 src0_sel:WORD_1
	v_cvt_pk_f32_fp8_sdwa v[232:233], v127 src0_sel:WORD_1
	v_pk_fma_f32 v[250:251], v[218:219], v[152:153], v[250:251]
	v_pk_fma_f32 v[252:253], v[226:227], v[152:153], v[252:253]
	v_pk_fma_f32 v[250:251], v[220:221], v[154:155], v[250:251]
	v_pk_fma_f32 v[252:253], v[228:229], v[154:155], v[252:253]
	v_pk_fma_f32 v[250:251], v[222:223], v[156:157], v[250:251]
	v_pk_fma_f32 v[252:253], v[230:231], v[156:157], v[252:253]
	v_pk_fma_f32 v[250:251], v[224:225], v[158:159], v[250:251]
	v_pk_fma_f32 v[252:253], v[232:233], v[158:159], v[252:253]
	v_add_f32_e32 v216, v250, v251
	v_add_f32_e32 v217, v252, v253
	s_lshl_b32 s34, s20, 9
	s_add_u32 s32, s12, s34
	s_addc_u32 s33, s13, 0
	s_nop 1
	v_add_f32_dpp v218, v202, v202 row_half_mirror row_mask:0xf bank_mask:0x5
	v_add_f32_dpp v219, v203, v203 row_half_mirror row_mask:0xf bank_mask:0x5
	v_add_f32_dpp v220, v204, v204 row_half_mirror row_mask:0xf bank_mask:0x5
	v_add_f32_dpp v221, v205, v205 row_half_mirror row_mask:0xf bank_mask:0x5
	v_add_f32_dpp v222, v206, v206 row_half_mirror row_mask:0xf bank_mask:0x5
	v_add_f32_dpp v223, v207, v207 row_half_mirror row_mask:0xf bank_mask:0x5
	v_add_f32_dpp v224, v208, v208 row_half_mirror row_mask:0xf bank_mask:0x5
	v_add_f32_dpp v225, v209, v209 row_half_mirror row_mask:0xf bank_mask:0x5
	v_add_f32_dpp v218, v210, v210 row_half_mirror row_mask:0xf bank_mask:0xa
	v_add_f32_dpp v219, v211, v211 row_half_mirror row_mask:0xf bank_mask:0xa
	v_add_f32_dpp v220, v212, v212 row_half_mirror row_mask:0xf bank_mask:0xa
	v_add_f32_dpp v221, v213, v213 row_half_mirror row_mask:0xf bank_mask:0xa
	v_add_f32_dpp v222, v214, v214 row_half_mirror row_mask:0xf bank_mask:0xa
	v_add_f32_dpp v223, v215, v215 row_half_mirror row_mask:0xf bank_mask:0xa
	v_add_f32_dpp v224, v216, v216 row_half_mirror row_mask:0xf bank_mask:0xa
	v_add_f32_dpp v225, v217, v217 row_half_mirror row_mask:0xf bank_mask:0xa
	v_cndmask_b32_e64 v226, v218, v222, s[26:27]
	v_cndmask_b32_e64 v227, v219, v223, s[26:27]
	v_cndmask_b32_e64 v228, v220, v224, s[26:27]
	v_cndmask_b32_e64 v229, v221, v225, s[26:27]
	v_cndmask_b32_e64 v230, v222, v218, s[26:27]
	v_cndmask_b32_e64 v231, v223, v219, s[26:27]
	v_cndmask_b32_e64 v232, v224, v220, s[26:27]
	v_cndmask_b32_e64 v233, v225, v221, s[26:27]
	s_nop 0
	v_add_f32_dpp v250, v230, v226 quad_perm:[2,3,0,1] row_mask:0xf bank_mask:0xf
	v_add_f32_dpp v251, v231, v227 quad_perm:[2,3,0,1] row_mask:0xf bank_mask:0xf
	v_add_f32_dpp v252, v232, v228 quad_perm:[2,3,0,1] row_mask:0xf bank_mask:0xf
	v_add_f32_dpp v253, v233, v229 quad_perm:[2,3,0,1] row_mask:0xf bank_mask:0xf
	v_cndmask_b32_e64 v226, v250, v252, s[28:29]
	v_cndmask_b32_e64 v227, v251, v253, s[28:29]
	v_cndmask_b32_e64 v230, v252, v250, s[28:29]
	v_cndmask_b32_e64 v231, v253, v251, s[28:29]
	s_nop 1
	v_add_f32_dpp v218, v230, v226 quad_perm:[1,0,3,2] row_mask:0xf bank_mask:0xf
	v_add_f32_dpp v219, v231, v227 quad_perm:[1,0,3,2] row_mask:0xf bank_mask:0xf
	global_store_dwordx2 v180, v[218:219], s[32:33]
	s_add_u32 s20, s20, s21
	s_cmp_lt_u32 s20, 0x4000
	s_cbranch_scc0 .Lgd_done_L0
	s_add_u32 s36, s20, s21
	s_add_u32 s37, s36, s21
	s_add_u32 s37, s37, s21
	s_min_u32 s36, s36, 0x3fff
	s_min_u32 s37, s37, 0x3fff
	s_waitcnt vmcnt(25)
	v_lshl_or_b32 v234, v234, 7, v176
	v_lshl_or_b32 v235, v235, 7, v176
	v_lshl_or_b32 v236, v236, 7, v176
	v_lshl_or_b32 v237, v237, 7, v176
	v_lshl_or_b32 v238, v238, 7, v176
	v_lshl_or_b32 v239, v239, 7, v176
	v_lshl_or_b32 v240, v240, 7, v176
	v_lshl_or_b32 v241, v241, 7, v176
	v_lshl_or_b32 v242, v242, 7, v176
	v_lshl_or_b32 v243, v243, 7, v176
	v_lshl_or_b32 v244, v244, 7, v176
	v_lshl_or_b32 v245, v245, 7, v176
	v_lshl_or_b32 v246, v246, 7, v176
	v_lshl_or_b32 v247, v247, 7, v176
	v_lshl_or_b32 v248, v248, 7, v176
	v_lshl_or_b32 v249, v249, 7, v176
	s_lshl_b32 s34, s36, 12
	s_add_u32 s24, s4, s34
	s_addc_u32 s25, s5, 0
	global_load_dwordx4 v[144:147], v177, s[24:25] offset:0
	global_load_dwordx4 v[148:151], v177, s[24:25] offset:16
	global_load_dwordx4 v[152:155], v177, s[24:25] offset:32
	global_load_dwordx4 v[156:159], v177, s[24:25] offset:48
	global_load_dwordx4 v[64:67], v234, s[2:3]
	global_load_dwordx4 v[68:71], v235, s[2:3]
	global_load_dwordx4 v[72:75], v236, s[2:3]
	global_load_dwordx4 v[76:79], v237, s[2:3]
	global_load_dwordx4 v[80:83], v238, s[2:3]
	global_load_dwordx4 v[84:87], v239, s[2:3]
	global_load_dwordx4 v[88:91], v240, s[2:3]
	global_load_dwordx4 v[92:95], v241, s[2:3]
	global_load_dwordx4 v[96:99], v242, s[2:3]
	global_load_dwordx4 v[100:103], v243, s[2:3]
	global_load_dwordx4 v[104:107], v244, s[2:3]
	global_load_dwordx4 v[108:111], v245, s[2:3]
	global_load_dwordx4 v[112:115], v246, s[2:3]
	global_load_dwordx4 v[116:119], v247, s[2:3]
	global_load_dwordx4 v[120:123], v248, s[2:3]
	global_load_dwordx4 v[124:127], v249, s[2:3]
	s_lshl_b32 s34, s37, 9
	s_add_u32 s22, s6, s34
	s_addc_u32 s23, s7, 0
	global_load_dwordx4 v[186:189], v181, s[22:23] offset:0
	global_load_dwordx4 v[190:193], v181, s[22:23] offset:16
	global_load_dwordx4 v[194:197], v181, s[22:23] offset:32
	global_load_dwordx4 v[198:201], v181, s[22:23] offset:48
	s_waitcnt vmcnt(29)
	v_cvt_pk_f32_fp8_e32 v[218:219], v0
	v_cvt_pk_f32_fp8_e32 v[226:227], v4
	v_cvt_pk_f32_fp8_sdwa v[220:221], v0 src0_sel:WORD_1
	v_cvt_pk_f32_fp8_sdwa v[228:229], v4 src0_sel:WORD_1
	v_cvt_pk_f32_fp8_e32 v[222:223], v1
	v_cvt_pk_f32_fp8_e32 v[230:231], v5
	v_cvt_pk_f32_fp8_sdwa v[224:225], v1 src0_sel:WORD_1
	v_cvt_pk_f32_fp8_sdwa v[232:233], v5 src0_sel:WORD_1
	v_pk_mul_f32 v[250:251], v[218:219], v[128:129]
	v_pk_mul_f32 v[252:253], v[226:227], v[128:129]
	v_pk_fma_f32 v[250:251], v[220:221], v[130:131], v[250:251]
	v_pk_fma_f32 v[252:253], v[228:229], v[130:131], v[252:253]
	v_pk_fma_f32 v[250:251], v[222:223], v[132:133], v[250:251]
	v_pk_fma_f32 v[252:253], v[230:231], v[132:133], v[252:253]
	v_pk_fma_f32 v[250:251], v[224:225], v[134:135], v[250:251]
	v_pk_fma_f32 v[252:253], v[232:233], v[134:135], v[252:253]
	v_cvt_pk_f32_fp8_e32 v[218:219], v2
	v_cvt_pk_f32_fp8_e32 v[226:227], v6
	v_cvt_pk_f32_fp8_sdwa v[220:221], v2 src0_sel:WORD_1
	v_cvt_pk_f32_fp8_sdwa v[228:229], v6 src0_sel:WORD_1
	v_cvt_pk_f32_fp8_e32 v[222:223], v3
	v_cvt_pk_f32_fp8_e32 v[230:231], v7
	v_cvt_pk_f32_fp8_sdwa v[224:225], v3 src0_sel:WORD_1
	v_cvt_pk_f32_fp8_sdwa v[232:233], v7 src0_sel:WORD_1
	v_pk_fma_f32 v[250:251], v[218:219], v[136:137], v[250:251]
	v_pk_fma_f32 v[252:253], v[226:227], v[136:137], v[252:253]
	v_pk_fma_f32 v[250:251], v[220:221], v[138:139], v[250:251]
	v_pk_fma_f32 v[252:253], v[228:229], v[138:139], v[252:253]
	v_pk_fma_f32 v[250:251], v[222:223], v[140:141], v[250:251]
	v_pk_fma_f32 v[252:253], v[230:231], v[140:141], v[252:253]
	v_pk_fma_f32 v[250:251], v[224:225], v[142:143], v[250:251]
	v_pk_fma_f32 v[252:253], v[232:233], v[142:143], v[252:253]
	v_add_f32_e32 v202, v250, v251
	v_add_f32_e32 v203, v252, v253
	v_cvt_pk_f32_fp8_e32 v[218:219], v8
	v_cvt_pk_f32_fp8_e32 v[226:227], v12
	v_cvt_pk_f32_fp8_sdwa v[220:221], v8 src0_sel:WORD_1
	v_cvt_pk_f32_fp8_sdwa v[228:229], v12 src0_sel:WORD_1
	v_cvt_pk_f32_fp8_e32 v[222:223], v9
	v_cvt_pk_f32_fp8_e32 v[230:231], v13
	v_cvt_pk_f32_fp8_sdwa v[224:225], v9 src0_sel:WORD_1
	v_cvt_pk_f32_fp8_sdwa v[232:233], v13 src0_sel:WORD_1
	v_pk_mul_f32 v[250:251], v[218:219], v[128:129]
	v_pk_mul_f32 v[252:253], v[226:227], v[128:129]
	v_pk_fma_f32 v[250:251], v[220:221], v[130:131], v[250:251]
	v_pk_fma_f32 v[252:253], v[228:229], v[130:131], v[252:253]
	v_pk_fma_f32 v[250:251], v[222:223], v[132:133], v[250:251]
	v_pk_fma_f32 v[252:253], v[230:231], v[132:133], v[252:253]
	v_pk_fma_f32 v[250:251], v[224:225], v[134:135], v[250:251]
	v_pk_fma_f32 v[252:253], v[232:233], v[134:135], v[252:253]
	v_cvt_pk_f32_fp8_e32 v[218:219], v10
	v_cvt_pk_f32_fp8_e32 v[226:227], v14
	v_cvt_pk_f32_fp8_sdwa v[220:221], v10 src0_sel:WORD_1
	v_cvt_pk_f32_fp8_sdwa v[228:229], v14 src0_sel:WORD_1
	v_cvt_pk_f32_fp8_e32 v[222:223], v11
	v_cvt_pk_f32_fp8_e32 v[230:231], v15
	v_cvt_pk_f32_fp8_sdwa v[224:225], v11 src0_sel:WORD_1
	v_cvt_pk_f32_fp8_sdwa v[232:233], v15 src0_sel:WORD_1
	v_pk_fma_f32 v[250:251], v[218:219], v[136:137], v[250:251]
	v_pk_fma_f32 v[252:253], v[226:227], v[136:137], v[252:253]
	v_pk_fma_f32 v[250:251], v[220:221], v[138:139], v[250:251]
	v_pk_fma_f32 v[252:253], v[228:229], v[138:139], v[252:253]
	v_pk_fma_f32 v[250:251], v[222:223], v[140:141], v[250:251]
	v_pk_fma_f32 v[252:253], v[230:231], v[140:141], v[252:253]
	v_pk_fma_f32 v[250:251], v[224:225], v[142:143], v[250:251]
	v_pk_fma_f32 v[252:253], v[232:233], v[142:143], v[252:253]
	v_add_f32_e32 v204, v250, v251
	v_add_f32_e32 v205, v252, v253
	v_cvt_pk_f32_fp8_e32 v[218:219], v16
	v_cvt_pk_f32_fp8_e32 v[226:227], v20
	v_cvt_pk_f32_fp8_sdwa v[220:221], v16 src0_sel:WORD_1
	v_cvt_pk_f32_fp8_sdwa v[228:229], v20 src0_sel:WORD_1
	v_cvt_pk_f32_fp8_e32 v[222:223], v17
	v_cvt_pk_f32_fp8_e32 v[230:231], v21
	v_cvt_pk_f32_fp8_sdwa v[224:225], v17 src0_sel:WORD_1
	v_cvt_pk_f32_fp8_sdwa v[232:233], v21 src0_sel:WORD_1
	v_pk_mul_f32 v[250:251], v[218:219], v[128:129]
	v_pk_mul_f32 v[252:253], v[226:227], v[128:129]
	v_pk_fma_f32 v[250:251], v[220:221], v[130:131], v[250:251]
	v_pk_fma_f32 v[252:253], v[228:229], v[130:131], v[252:253]
	v_pk_fma_f32 v[250:251], v[222:223], v[132:133], v[250:251]
	v_pk_fma_f32 v[252:253], v[230:231], v[132:133], v[252:253]
	v_pk_fma_f32 v[250:251], v[224:225], v[134:135], v[250:251]
	v_pk_fma_f32 v[252:253], v[232:233], v[134:135], v[252:253]
	v_cvt_pk_f32_fp8_e32 v[218:219], v18
	v_cvt_pk_f32_fp8_e32 v[226:227], v22
	v_cvt_pk_f32_fp8_sdwa v[220:221], v18 src0_sel:WORD_1
	v_cvt_pk_f32_fp8_sdwa v[228:229], v22 src0_sel:WORD_1
	v_cvt_pk_f32_fp8_e32 v[222:223], v19
	v_cvt_pk_f32_fp8_e32 v[230:231], v23
	v_cvt_pk_f32_fp8_sdwa v[224:225], v19 src0_sel:WORD_1
	v_cvt_pk_f32_fp8_sdwa v[232:233], v23 src0_sel:WORD_1
	v_pk_fma_f32 v[250:251], v[218:219], v[136:137], v[250:251]
	v_pk_fma_f32 v[252:253], v[226:227], v[136:137], v[252:253]
	v_pk_fma_f32 v[250:251], v[220:221], v[138:139], v[250:251]
	v_pk_fma_f32 v[252:253], v[228:229], v[138:139], v[252:253]
	v_pk_fma_f32 v[250:251], v[222:223], v[140:141], v[250:251]
	v_pk_fma_f32 v[252:253], v[230:231], v[140:141], v[252:253]
	v_pk_fma_f32 v[250:251], v[224:225], v[142:143], v[250:251]
	v_pk_fma_f32 v[252:253], v[232:233], v[142:143], v[252:253]
	v_add_f32_e32 v206, v250, v251
	v_add_f32_e32 v207, v252, v253
	v_cvt_pk_f32_fp8_e32 v[218:219], v24
	v_cvt_pk_f32_fp8_e32 v[226:227], v28
	v_cvt_pk_f32_fp8_sdwa v[220:221], v24 src0_sel:WORD_1
	v_cvt_pk_f32_fp8_sdwa v[228:229], v28 src0_sel:WORD_1
	v_cvt_pk_f32_fp8_e32 v[222:223], v25
	v_cvt_pk_f32_fp8_e32 v[230:231], v29
	v_cvt_pk_f32_fp8_sdwa v[224:225], v25 src0_sel:WORD_1
	v_cvt_pk_f32_fp8_sdwa v[232:233], v29 src0_sel:WORD_1
	v_pk_mul_f32 v[250:251], v[218:219], v[128:129]
	v_pk_mul_f32 v[252:253], v[226:227], v[128:129]
	v_pk_fma_f32 v[250:251], v[220:221], v[130:131], v[250:251]
	v_pk_fma_f32 v[252:253], v[228:229], v[130:131], v[252:253]
	v_pk_fma_f32 v[250:251], v[222:223], v[132:133], v[250:251]
	v_pk_fma_f32 v[252:253], v[230:231], v[132:133], v[252:253]
	v_pk_fma_f32 v[250:251], v[224:225], v[134:135], v[250:251]
	v_pk_fma_f32 v[252:253], v[232:233], v[134:135], v[252:253]
	v_cvt_pk_f32_fp8_e32 v[218:219], v26
	v_cvt_pk_f32_fp8_e32 v[226:227], v30
	v_cvt_pk_f32_fp8_sdwa v[220:221], v26 src0_sel:WORD_1
	v_cvt_pk_f32_fp8_sdwa v[228:229], v30 src0_sel:WORD_1
	v_cvt_pk_f32_fp8_e32 v[222:223], v27
	v_cvt_pk_f32_fp8_e32 v[230:231], v31
	v_cvt_pk_f32_fp8_sdwa v[224:225], v27 src0_sel:WORD_1
	v_cvt_pk_f32_fp8_sdwa v[232:233], v31 src0_sel:WORD_1
	v_pk_fma_f32 v[250:251], v[218:219], v[136:137], v[250:251]
	v_pk_fma_f32 v[252:253], v[226:227], v[136:137], v[252:253]
	v_pk_fma_f32 v[250:251], v[220:221], v[138:139], v[250:251]
	v_pk_fma_f32 v[252:253], v[228:229], v[138:139], v[252:253]
	v_pk_fma_f32 v[250:251], v[222:223], v[140:141], v[250:251]
	v_pk_fma_f32 v[252:253], v[230:231], v[140:141], v[252:253]
	v_pk_fma_f32 v[250:251], v[224:225], v[142:143], v[250:251]
	v_pk_fma_f32 v[252:253], v[232:233], v[142:143], v[252:253]
	v_add_f32_e32 v208, v250, v251
	v_add_f32_e32 v209, v252, v253
	v_cvt_pk_f32_fp8_e32 v[218:219], v32
	v_cvt_pk_f32_fp8_e32 v[226:227], v36
	v_cvt_pk_f32_fp8_sdwa v[220:221], v32 src0_sel:WORD_1
	v_cvt_pk_f32_fp8_sdwa v[228:229], v36 src0_sel:WORD_1
	v_cvt_pk_f32_fp8_e32 v[222:223], v33
	v_cvt_pk_f32_fp8_e32 v[230:231], v37
	v_cvt_pk_f32_fp8_sdwa v[224:225], v33 src0_sel:WORD_1
	v_cvt_pk_f32_fp8_sdwa v[232:233], v37 src0_sel:WORD_1
	v_pk_mul_f32 v[250:251], v[218:219], v[128:129]
	v_pk_mul_f32 v[252:253], v[226:227], v[128:129]
	v_pk_fma_f32 v[250:251], v[220:221], v[130:131], v[250:251]
	v_pk_fma_f32 v[252:253], v[228:229], v[130:131], v[252:253]
	v_pk_fma_f32 v[250:251], v[222:223], v[132:133], v[250:251]
	v_pk_fma_f32 v[252:253], v[230:231], v[132:133], v[252:253]
	v_pk_fma_f32 v[250:251], v[224:225], v[134:135], v[250:251]
	v_pk_fma_f32 v[252:253], v[232:233], v[134:135], v[252:253]
	v_cvt_pk_f32_fp8_e32 v[218:219], v34
	v_cvt_pk_f32_fp8_e32 v[226:227], v38
	v_cvt_pk_f32_fp8_sdwa v[220:221], v34 src0_sel:WORD_1
	v_cvt_pk_f32_fp8_sdwa v[228:229], v38 src0_sel:WORD_1
	v_cvt_pk_f32_fp8_e32 v[222:223], v35
	v_cvt_pk_f32_fp8_e32 v[230:231], v39
	v_cvt_pk_f32_fp8_sdwa v[224:225], v35 src0_sel:WORD_1
	v_cvt_pk_f32_fp8_sdwa v[232:233], v39 src0_sel:WORD_1
	v_pk_fma_f32 v[250:251], v[218:219], v[136:137], v[250:251]
	v_pk_fma_f32 v[252:253], v[226:227], v[136:137], v[252:253]
	v_pk_fma_f32 v[250:251], v[220:221], v[138:139], v[250:251]
	v_pk_fma_f32 v[252:253], v[228:229], v[138:139], v[252:253]
	v_pk_fma_f32 v[250:251], v[222:223], v[140:141], v[250:251]
	v_pk_fma_f32 v[252:253], v[230:231], v[140:141], v[252:253]
	v_pk_fma_f32 v[250:251], v[224:225], v[142:143], v[250:251]
	v_pk_fma_f32 v[252:253], v[232:233], v[142:143], v[252:253]
	v_add_f32_e32 v210, v250, v251
	v_add_f32_e32 v211, v252, v253
	v_cvt_pk_f32_fp8_e32 v[218:219], v40
	v_cvt_pk_f32_fp8_e32 v[226:227], v44
	v_cvt_pk_f32_fp8_sdwa v[220:221], v40 src0_sel:WORD_1
	v_cvt_pk_f32_fp8_sdwa v[228:229], v44 src0_sel:WORD_1
	v_cvt_pk_f32_fp8_e32 v[222:223], v41
	v_cvt_pk_f32_fp8_e32 v[230:231], v45
	v_cvt_pk_f32_fp8_sdwa v[224:225], v41 src0_sel:WORD_1
	v_cvt_pk_f32_fp8_sdwa v[232:233], v45 src0_sel:WORD_1
	v_pk_mul_f32 v[250:251], v[218:219], v[128:129]
	v_pk_mul_f32 v[252:253], v[226:227], v[128:129]
	v_pk_fma_f32 v[250:251], v[220:221], v[130:131], v[250:251]
	v_pk_fma_f32 v[252:253], v[228:229], v[130:131], v[252:253]
	v_pk_fma_f32 v[250:251], v[222:223], v[132:133], v[250:251]
	v_pk_fma_f32 v[252:253], v[230:231], v[132:133], v[252:253]
	v_pk_fma_f32 v[250:251], v[224:225], v[134:135], v[250:251]
	v_pk_fma_f32 v[252:253], v[232:233], v[134:135], v[252:253]
	v_cvt_pk_f32_fp8_e32 v[218:219], v42
	v_cvt_pk_f32_fp8_e32 v[226:227], v46
	v_cvt_pk_f32_fp8_sdwa v[220:221], v42 src0_sel:WORD_1
	v_cvt_pk_f32_fp8_sdwa v[228:229], v46 src0_sel:WORD_1
	v_cvt_pk_f32_fp8_e32 v[222:223], v43
	v_cvt_pk_f32_fp8_e32 v[230:231], v47
	v_cvt_pk_f32_fp8_sdwa v[224:225], v43 src0_sel:WORD_1
	v_cvt_pk_f32_fp8_sdwa v[232:233], v47 src0_sel:WORD_1
	v_pk_fma_f32 v[250:251], v[218:219], v[136:137], v[250:251]
	v_pk_fma_f32 v[252:253], v[226:227], v[136:137], v[252:253]
	v_pk_fma_f32 v[250:251], v[220:221], v[138:139], v[250:251]
	v_pk_fma_f32 v[252:253], v[228:229], v[138:139], v[252:253]
	v_pk_fma_f32 v[250:251], v[222:223], v[140:141], v[250:251]
	v_pk_fma_f32 v[252:253], v[230:231], v[140:141], v[252:253]
	v_pk_fma_f32 v[250:251], v[224:225], v[142:143], v[250:251]
	v_pk_fma_f32 v[252:253], v[232:233], v[142:143], v[252:253]
	v_add_f32_e32 v212, v250, v251
	v_add_f32_e32 v213, v252, v253
	v_cvt_pk_f32_fp8_e32 v[218:219], v48
	v_cvt_pk_f32_fp8_e32 v[226:227], v52
	v_cvt_pk_f32_fp8_sdwa v[220:221], v48 src0_sel:WORD_1
	v_cvt_pk_f32_fp8_sdwa v[228:229], v52 src0_sel:WORD_1
	v_cvt_pk_f32_fp8_e32 v[222:223], v49
	v_cvt_pk_f32_fp8_e32 v[230:231], v53
	v_cvt_pk_f32_fp8_sdwa v[224:225], v49 src0_sel:WORD_1
	v_cvt_pk_f32_fp8_sdwa v[232:233], v53 src0_sel:WORD_1
	v_pk_mul_f32 v[250:251], v[218:219], v[128:129]
	v_pk_mul_f32 v[252:253], v[226:227], v[128:129]
	v_pk_fma_f32 v[250:251], v[220:221], v[130:131], v[250:251]
	v_pk_fma_f32 v[252:253], v[228:229], v[130:131], v[252:253]
	v_pk_fma_f32 v[250:251], v[222:223], v[132:133], v[250:251]
	v_pk_fma_f32 v[252:253], v[230:231], v[132:133], v[252:253]
	v_pk_fma_f32 v[250:251], v[224:225], v[134:135], v[250:251]
	v_pk_fma_f32 v[252:253], v[232:233], v[134:135], v[252:253]
	v_cvt_pk_f32_fp8_e32 v[218:219], v50
	v_cvt_pk_f32_fp8_e32 v[226:227], v54
	v_cvt_pk_f32_fp8_sdwa v[220:221], v50 src0_sel:WORD_1
	v_cvt_pk_f32_fp8_sdwa v[228:229], v54 src0_sel:WORD_1
	v_cvt_pk_f32_fp8_e32 v[222:223], v51
	v_cvt_pk_f32_fp8_e32 v[230:231], v55
	v_cvt_pk_f32_fp8_sdwa v[224:225], v51 src0_sel:WORD_1
	v_cvt_pk_f32_fp8_sdwa v[232:233], v55 src0_sel:WORD_1
	v_pk_fma_f32 v[250:251], v[218:219], v[136:137], v[250:251]
	v_pk_fma_f32 v[252:253], v[226:227], v[136:137], v[252:253]
	v_pk_fma_f32 v[250:251], v[220:221], v[138:139], v[250:251]
	v_pk_fma_f32 v[252:253], v[228:229], v[138:139], v[252:253]
	v_pk_fma_f32 v[250:251], v[222:223], v[140:141], v[250:251]
	v_pk_fma_f32 v[252:253], v[230:231], v[140:141], v[252:253]
	v_pk_fma_f32 v[250:251], v[224:225], v[142:143], v[250:251]
	v_pk_fma_f32 v[252:253], v[232:233], v[142:143], v[252:253]
	v_add_f32_e32 v214, v250, v251
	v_add_f32_e32 v215, v252, v253
	v_cvt_pk_f32_fp8_e32 v[218:219], v56
	v_cvt_pk_f32_fp8_e32 v[226:227], v60
	v_cvt_pk_f32_fp8_sdwa v[220:221], v56 src0_sel:WORD_1
	v_cvt_pk_f32_fp8_sdwa v[228:229], v60 src0_sel:WORD_1
	v_cvt_pk_f32_fp8_e32 v[222:223], v57
	v_cvt_pk_f32_fp8_e32 v[230:231], v61
	v_cvt_pk_f32_fp8_sdwa v[224:225], v57 src0_sel:WORD_1
	v_cvt_pk_f32_fp8_sdwa v[232:233], v61 src0_sel:WORD_1
	v_pk_mul_f32 v[250:251], v[218:219], v[128:129]
	v_pk_mul_f32 v[252:253], v[226:227], v[128:129]
	v_pk_fma_f32 v[250:251], v[220:221], v[130:131], v[250:251]
	v_pk_fma_f32 v[252:253], v[228:229], v[130:131], v[252:253]
	v_pk_fma_f32 v[250:251], v[222:223], v[132:133], v[250:251]
	v_pk_fma_f32 v[252:253], v[230:231], v[132:133], v[252:253]
	v_pk_fma_f32 v[250:251], v[224:225], v[134:135], v[250:251]
	v_pk_fma_f32 v[252:253], v[232:233], v[134:135], v[252:253]
	v_cvt_pk_f32_fp8_e32 v[218:219], v58
	v_cvt_pk_f32_fp8_e32 v[226:227], v62
	v_cvt_pk_f32_fp8_sdwa v[220:221], v58 src0_sel:WORD_1
	v_cvt_pk_f32_fp8_sdwa v[228:229], v62 src0_sel:WORD_1
	v_cvt_pk_f32_fp8_e32 v[222:223], v59
	v_cvt_pk_f32_fp8_e32 v[230:231], v63
	v_cvt_pk_f32_fp8_sdwa v[224:225], v59 src0_sel:WORD_1
	v_cvt_pk_f32_fp8_sdwa v[232:233], v63 src0_sel:WORD_1
	v_pk_fma_f32 v[250:251], v[218:219], v[136:137], v[250:251]
	v_pk_fma_f32 v[252:253], v[226:227], v[136:137], v[252:253]
	v_pk_fma_f32 v[250:251], v[220:221], v[138:139], v[250:251]
	v_pk_fma_f32 v[252:253], v[228:229], v[138:139], v[252:253]
	v_pk_fma_f32 v[250:251], v[222:223], v[140:141], v[250:251]
	v_pk_fma_f32 v[252:253], v[230:231], v[140:141], v[252:253]
	v_pk_fma_f32 v[250:251], v[224:225], v[142:143], v[250:251]
	v_pk_fma_f32 v[252:253], v[232:233], v[142:143], v[252:253]
	v_add_f32_e32 v216, v250, v251
	v_add_f32_e32 v217, v252, v253
	s_lshl_b32 s34, s20, 9
	s_add_u32 s32, s12, s34
	s_addc_u32 s33, s13, 0
	s_nop 1
	v_add_f32_dpp v218, v202, v202 row_half_mirror row_mask:0xf bank_mask:0x5
	v_add_f32_dpp v219, v203, v203 row_half_mirror row_mask:0xf bank_mask:0x5
	v_add_f32_dpp v220, v204, v204 row_half_mirror row_mask:0xf bank_mask:0x5
	v_add_f32_dpp v221, v205, v205 row_half_mirror row_mask:0xf bank_mask:0x5
	v_add_f32_dpp v222, v206, v206 row_half_mirror row_mask:0xf bank_mask:0x5
	v_add_f32_dpp v223, v207, v207 row_half_mirror row_mask:0xf bank_mask:0x5
	v_add_f32_dpp v224, v208, v208 row_half_mirror row_mask:0xf bank_mask:0x5
	v_add_f32_dpp v225, v209, v209 row_half_mirror row_mask:0xf bank_mask:0x5
	v_add_f32_dpp v218, v210, v210 row_half_mirror row_mask:0xf bank_mask:0xa
	v_add_f32_dpp v219, v211, v211 row_half_mirror row_mask:0xf bank_mask:0xa
	v_add_f32_dpp v220, v212, v212 row_half_mirror row_mask:0xf bank_mask:0xa
	v_add_f32_dpp v221, v213, v213 row_half_mirror row_mask:0xf bank_mask:0xa
	v_add_f32_dpp v222, v214, v214 row_half_mirror row_mask:0xf bank_mask:0xa
	v_add_f32_dpp v223, v215, v215 row_half_mirror row_mask:0xf bank_mask:0xa
	v_add_f32_dpp v224, v216, v216 row_half_mirror row_mask:0xf bank_mask:0xa
	v_add_f32_dpp v225, v217, v217 row_half_mirror row_mask:0xf bank_mask:0xa
	v_cndmask_b32_e64 v226, v218, v222, s[26:27]
	v_cndmask_b32_e64 v227, v219, v223, s[26:27]
	v_cndmask_b32_e64 v228, v220, v224, s[26:27]
	v_cndmask_b32_e64 v229, v221, v225, s[26:27]
	v_cndmask_b32_e64 v230, v222, v218, s[26:27]
	v_cndmask_b32_e64 v231, v223, v219, s[26:27]
	v_cndmask_b32_e64 v232, v224, v220, s[26:27]
	v_cndmask_b32_e64 v233, v225, v221, s[26:27]
	s_nop 0
	v_add_f32_dpp v250, v230, v226 quad_perm:[2,3,0,1] row_mask:0xf bank_mask:0xf
	v_add_f32_dpp v251, v231, v227 quad_perm:[2,3,0,1] row_mask:0xf bank_mask:0xf
	v_add_f32_dpp v252, v232, v228 quad_perm:[2,3,0,1] row_mask:0xf bank_mask:0xf
	v_add_f32_dpp v253, v233, v229 quad_perm:[2,3,0,1] row_mask:0xf bank_mask:0xf
	v_cndmask_b32_e64 v226, v250, v252, s[28:29]
	v_cndmask_b32_e64 v227, v251, v253, s[28:29]
	v_cndmask_b32_e64 v230, v252, v250, s[28:29]
	v_cndmask_b32_e64 v231, v253, v251, s[28:29]
	s_nop 1
	v_add_f32_dpp v218, v230, v226 quad_perm:[1,0,3,2] row_mask:0xf bank_mask:0xf
	v_add_f32_dpp v219, v231, v227 quad_perm:[1,0,3,2] row_mask:0xf bank_mask:0xf
	global_store_dwordx2 v180, v[218:219], s[32:33]
	s_add_u32 s20, s20, s21
	s_cmp_lt_u32 s20, 0x4000
	s_cbranch_scc0 .Lgd_done_L0
	s_add_u32 s36, s20, s21
	s_add_u32 s37, s36, s21
	s_add_u32 s37, s37, s21
	s_min_u32 s36, s36, 0x3fff
	s_min_u32 s37, s37, 0x3fff
	s_waitcnt vmcnt(25)
	v_lshl_or_b32 v160, v160, 7, v176
	v_lshl_or_b32 v161, v161, 7, v176
	v_lshl_or_b32 v162, v162, 7, v176
	v_lshl_or_b32 v163, v163, 7, v176
	v_lshl_or_b32 v164, v164, 7, v176
	v_lshl_or_b32 v165, v165, 7, v176
	v_lshl_or_b32 v166, v166, 7, v176
	v_lshl_or_b32 v167, v167, 7, v176
	v_lshl_or_b32 v168, v168, 7, v176
	v_lshl_or_b32 v169, v169, 7, v176
	v_lshl_or_b32 v170, v170, 7, v176
	v_lshl_or_b32 v171, v171, 7, v176
	v_lshl_or_b32 v172, v172, 7, v176
	v_lshl_or_b32 v173, v173, 7, v176
	v_lshl_or_b32 v174, v174, 7, v176
	v_lshl_or_b32 v175, v175, 7, v176
	s_lshl_b32 s34, s36, 12
	s_add_u32 s24, s4, s34
	s_addc_u32 s25, s5, 0
	global_load_dwordx4 v[128:131], v177, s[24:25] offset:0
	global_load_dwordx4 v[132:135], v177, s[24:25] offset:16
	global_load_dwordx4 v[136:139], v177, s[24:25] offset:32
	global_load_dwordx4 v[140:143], v177, s[24:25] offset:48
	global_load_dwordx4 v[0:3], v160, s[2:3]
	global_load_dwordx4 v[4:7], v161, s[2:3]
	global_load_dwordx4 v[8:11], v162, s[2:3]
	global_load_dwordx4 v[12:15], v163, s[2:3]
	global_load_dwordx4 v[16:19], v164, s[2:3]
	global_load_dwordx4 v[20:23], v165, s[2:3]
	global_load_dwordx4 v[24:27], v166, s[2:3]
	global_load_dwordx4 v[28:31], v167, s[2:3]
	global_load_dwordx4 v[32:35], v168, s[2:3]
	global_load_dwordx4 v[36:39], v169, s[2:3]
	global_load_dwordx4 v[40:43], v170, s[2:3]
	global_load_dwordx4 v[44:47], v171, s[2:3]
	global_load_dwordx4 v[48:51], v172, s[2:3]
	global_load_dwordx4 v[52:55], v173, s[2:3]
	global_load_dwordx4 v[56:59], v174, s[2:3]
	global_load_dwordx4 v[60:63], v175, s[2:3]
	s_lshl_b32 s34, s37, 9
	s_add_u32 s22, s6, s34
	s_addc_u32 s23, s7, 0
	global_load_dwordx4 v[234:237], v181, s[22:23] offset:0
	global_load_dwordx4 v[238:241], v181, s[22:23] offset:16
	global_load_dwordx4 v[242:245], v181, s[22:23] offset:32
	global_load_dwordx4 v[246:249], v181, s[22:23] offset:48
	s_waitcnt vmcnt(29)
	v_cvt_pk_f32_fp8_e32 v[218:219], v64
	v_cvt_pk_f32_fp8_e32 v[226:227], v68
	v_cvt_pk_f32_fp8_sdwa v[220:221], v64 src0_sel:WORD_1
	v_cvt_pk_f32_fp8_sdwa v[228:229], v68 src0_sel:WORD_1
	v_cvt_pk_f32_fp8_e32 v[222:223], v65
	v_cvt_pk_f32_fp8_e32 v[230:231], v69
	v_cvt_pk_f32_fp8_sdwa v[224:225], v65 src0_sel:WORD_1
	v_cvt_pk_f32_fp8_sdwa v[232:233], v69 src0_sel:WORD_1
	v_pk_mul_f32 v[250:251], v[218:219], v[144:145]
	v_pk_mul_f32 v[252:253], v[226:227], v[144:145]
	v_pk_fma_f32 v[250:251], v[220:221], v[146:147], v[250:251]
	v_pk_fma_f32 v[252:253], v[228:229], v[146:147], v[252:253]
	v_pk_fma_f32 v[250:251], v[222:223], v[148:149], v[250:251]
	v_pk_fma_f32 v[252:253], v[230:231], v[148:149], v[252:253]
	v_pk_fma_f32 v[250:251], v[224:225], v[150:151], v[250:251]
	v_pk_fma_f32 v[252:253], v[232:233], v[150:151], v[252:253]
	v_cvt_pk_f32_fp8_e32 v[218:219], v66
	v_cvt_pk_f32_fp8_e32 v[226:227], v70
	v_cvt_pk_f32_fp8_sdwa v[220:221], v66 src0_sel:WORD_1
	v_cvt_pk_f32_fp8_sdwa v[228:229], v70 src0_sel:WORD_1
	v_cvt_pk_f32_fp8_e32 v[222:223], v67
	v_cvt_pk_f32_fp8_e32 v[230:231], v71
	v_cvt_pk_f32_fp8_sdwa v[224:225], v67 src0_sel:WORD_1
	v_cvt_pk_f32_fp8_sdwa v[232:233], v71 src0_sel:WORD_1
	v_pk_fma_f32 v[250:251], v[218:219], v[152:153], v[250:251]
	v_pk_fma_f32 v[252:253], v[226:227], v[152:153], v[252:253]
	v_pk_fma_f32 v[250:251], v[220:221], v[154:155], v[250:251]
	v_pk_fma_f32 v[252:253], v[228:229], v[154:155], v[252:253]
	v_pk_fma_f32 v[250:251], v[222:223], v[156:157], v[250:251]
	v_pk_fma_f32 v[252:253], v[230:231], v[156:157], v[252:253]
	v_pk_fma_f32 v[250:251], v[224:225], v[158:159], v[250:251]
	v_pk_fma_f32 v[252:253], v[232:233], v[158:159], v[252:253]
	v_add_f32_e32 v202, v250, v251
	v_add_f32_e32 v203, v252, v253
	v_cvt_pk_f32_fp8_e32 v[218:219], v72
	v_cvt_pk_f32_fp8_e32 v[226:227], v76
	v_cvt_pk_f32_fp8_sdwa v[220:221], v72 src0_sel:WORD_1
	v_cvt_pk_f32_fp8_sdwa v[228:229], v76 src0_sel:WORD_1
	v_cvt_pk_f32_fp8_e32 v[222:223], v73
	v_cvt_pk_f32_fp8_e32 v[230:231], v77
	v_cvt_pk_f32_fp8_sdwa v[224:225], v73 src0_sel:WORD_1
	v_cvt_pk_f32_fp8_sdwa v[232:233], v77 src0_sel:WORD_1
	v_pk_mul_f32 v[250:251], v[218:219], v[144:145]
	v_pk_mul_f32 v[252:253], v[226:227], v[144:145]
	v_pk_fma_f32 v[250:251], v[220:221], v[146:147], v[250:251]
	v_pk_fma_f32 v[252:253], v[228:229], v[146:147], v[252:253]
	v_pk_fma_f32 v[250:251], v[222:223], v[148:149], v[250:251]
	v_pk_fma_f32 v[252:253], v[230:231], v[148:149], v[252:253]
	v_pk_fma_f32 v[250:251], v[224:225], v[150:151], v[250:251]
	v_pk_fma_f32 v[252:253], v[232:233], v[150:151], v[252:253]
	v_cvt_pk_f32_fp8_e32 v[218:219], v74
	v_cvt_pk_f32_fp8_e32 v[226:227], v78
	v_cvt_pk_f32_fp8_sdwa v[220:221], v74 src0_sel:WORD_1
	v_cvt_pk_f32_fp8_sdwa v[228:229], v78 src0_sel:WORD_1
	v_cvt_pk_f32_fp8_e32 v[222:223], v75
	v_cvt_pk_f32_fp8_e32 v[230:231], v79
	v_cvt_pk_f32_fp8_sdwa v[224:225], v75 src0_sel:WORD_1
	v_cvt_pk_f32_fp8_sdwa v[232:233], v79 src0_sel:WORD_1
	v_pk_fma_f32 v[250:251], v[218:219], v[152:153], v[250:251]
	v_pk_fma_f32 v[252:253], v[226:227], v[152:153], v[252:253]
	v_pk_fma_f32 v[250:251], v[220:221], v[154:155], v[250:251]
	v_pk_fma_f32 v[252:253], v[228:229], v[154:155], v[252:253]
	v_pk_fma_f32 v[250:251], v[222:223], v[156:157], v[250:251]
	v_pk_fma_f32 v[252:253], v[230:231], v[156:157], v[252:253]
	v_pk_fma_f32 v[250:251], v[224:225], v[158:159], v[250:251]
	v_pk_fma_f32 v[252:253], v[232:233], v[158:159], v[252:253]
	v_add_f32_e32 v204, v250, v251
	v_add_f32_e32 v205, v252, v253
	v_cvt_pk_f32_fp8_e32 v[218:219], v80
	v_cvt_pk_f32_fp8_e32 v[226:227], v84
	v_cvt_pk_f32_fp8_sdwa v[220:221], v80 src0_sel:WORD_1
	v_cvt_pk_f32_fp8_sdwa v[228:229], v84 src0_sel:WORD_1
	v_cvt_pk_f32_fp8_e32 v[222:223], v81
	v_cvt_pk_f32_fp8_e32 v[230:231], v85
	v_cvt_pk_f32_fp8_sdwa v[224:225], v81 src0_sel:WORD_1
	v_cvt_pk_f32_fp8_sdwa v[232:233], v85 src0_sel:WORD_1
	v_pk_mul_f32 v[250:251], v[218:219], v[144:145]
	v_pk_mul_f32 v[252:253], v[226:227], v[144:145]
	v_pk_fma_f32 v[250:251], v[220:221], v[146:147], v[250:251]
	v_pk_fma_f32 v[252:253], v[228:229], v[146:147], v[252:253]
	v_pk_fma_f32 v[250:251], v[222:223], v[148:149], v[250:251]
	v_pk_fma_f32 v[252:253], v[230:231], v[148:149], v[252:253]
	v_pk_fma_f32 v[250:251], v[224:225], v[150:151], v[250:251]
	v_pk_fma_f32 v[252:253], v[232:233], v[150:151], v[252:253]
	v_cvt_pk_f32_fp8_e32 v[218:219], v82
	v_cvt_pk_f32_fp8_e32 v[226:227], v86
	v_cvt_pk_f32_fp8_sdwa v[220:221], v82 src0_sel:WORD_1
	v_cvt_pk_f32_fp8_sdwa v[228:229], v86 src0_sel:WORD_1
	v_cvt_pk_f32_fp8_e32 v[222:223], v83
	v_cvt_pk_f32_fp8_e32 v[230:231], v87
	v_cvt_pk_f32_fp8_sdwa v[224:225], v83 src0_sel:WORD_1
	v_cvt_pk_f32_fp8_sdwa v[232:233], v87 src0_sel:WORD_1
	v_pk_fma_f32 v[250:251], v[218:219], v[152:153], v[250:251]
	v_pk_fma_f32 v[252:253], v[226:227], v[152:153], v[252:253]
	v_pk_fma_f32 v[250:251], v[220:221], v[154:155], v[250:251]
	v_pk_fma_f32 v[252:253], v[228:229], v[154:155], v[252:253]
	v_pk_fma_f32 v[250:251], v[222:223], v[156:157], v[250:251]
	v_pk_fma_f32 v[252:253], v[230:231], v[156:157], v[252:253]
	v_pk_fma_f32 v[250:251], v[224:225], v[158:159], v[250:251]
	v_pk_fma_f32 v[252:253], v[232:233], v[158:159], v[252:253]
	v_add_f32_e32 v206, v250, v251
	v_add_f32_e32 v207, v252, v253
	v_cvt_pk_f32_fp8_e32 v[218:219], v88
	v_cvt_pk_f32_fp8_e32 v[226:227], v92
	v_cvt_pk_f32_fp8_sdwa v[220:221], v88 src0_sel:WORD_1
	v_cvt_pk_f32_fp8_sdwa v[228:229], v92 src0_sel:WORD_1
	v_cvt_pk_f32_fp8_e32 v[222:223], v89
	v_cvt_pk_f32_fp8_e32 v[230:231], v93
	v_cvt_pk_f32_fp8_sdwa v[224:225], v89 src0_sel:WORD_1
	v_cvt_pk_f32_fp8_sdwa v[232:233], v93 src0_sel:WORD_1
	v_pk_mul_f32 v[250:251], v[218:219], v[144:145]
	v_pk_mul_f32 v[252:253], v[226:227], v[144:145]
	v_pk_fma_f32 v[250:251], v[220:221], v[146:147], v[250:251]
	v_pk_fma_f32 v[252:253], v[228:229], v[146:147], v[252:253]
	v_pk_fma_f32 v[250:251], v[222:223], v[148:149], v[250:251]
	v_pk_fma_f32 v[252:253], v[230:231], v[148:149], v[252:253]
	v_pk_fma_f32 v[250:251], v[224:225], v[150:151], v[250:251]
	v_pk_fma_f32 v[252:253], v[232:233], v[150:151], v[252:253]
	v_cvt_pk_f32_fp8_e32 v[218:219], v90
	v_cvt_pk_f32_fp8_e32 v[226:227], v94
	v_cvt_pk_f32_fp8_sdwa v[220:221], v90 src0_sel:WORD_1
	v_cvt_pk_f32_fp8_sdwa v[228:229], v94 src0_sel:WORD_1
	v_cvt_pk_f32_fp8_e32 v[222:223], v91
	v_cvt_pk_f32_fp8_e32 v[230:231], v95
	v_cvt_pk_f32_fp8_sdwa v[224:225], v91 src0_sel:WORD_1
	v_cvt_pk_f32_fp8_sdwa v[232:233], v95 src0_sel:WORD_1
	v_pk_fma_f32 v[250:251], v[218:219], v[152:153], v[250:251]
	v_pk_fma_f32 v[252:253], v[226:227], v[152:153], v[252:253]
	v_pk_fma_f32 v[250:251], v[220:221], v[154:155], v[250:251]
	v_pk_fma_f32 v[252:253], v[228:229], v[154:155], v[252:253]
	v_pk_fma_f32 v[250:251], v[222:223], v[156:157], v[250:251]
	v_pk_fma_f32 v[252:253], v[230:231], v[156:157], v[252:253]
	v_pk_fma_f32 v[250:251], v[224:225], v[158:159], v[250:251]
	v_pk_fma_f32 v[252:253], v[232:233], v[158:159], v[252:253]
	v_add_f32_e32 v208, v250, v251
	v_add_f32_e32 v209, v252, v253
	v_cvt_pk_f32_fp8_e32 v[218:219], v96
	v_cvt_pk_f32_fp8_e32 v[226:227], v100
	v_cvt_pk_f32_fp8_sdwa v[220:221], v96 src0_sel:WORD_1
	v_cvt_pk_f32_fp8_sdwa v[228:229], v100 src0_sel:WORD_1
	v_cvt_pk_f32_fp8_e32 v[222:223], v97
	v_cvt_pk_f32_fp8_e32 v[230:231], v101
	v_cvt_pk_f32_fp8_sdwa v[224:225], v97 src0_sel:WORD_1
	v_cvt_pk_f32_fp8_sdwa v[232:233], v101 src0_sel:WORD_1
	v_pk_mul_f32 v[250:251], v[218:219], v[144:145]
	v_pk_mul_f32 v[252:253], v[226:227], v[144:145]
	v_pk_fma_f32 v[250:251], v[220:221], v[146:147], v[250:251]
	v_pk_fma_f32 v[252:253], v[228:229], v[146:147], v[252:253]
	v_pk_fma_f32 v[250:251], v[222:223], v[148:149], v[250:251]
	v_pk_fma_f32 v[252:253], v[230:231], v[148:149], v[252:253]
	v_pk_fma_f32 v[250:251], v[224:225], v[150:151], v[250:251]
	v_pk_fma_f32 v[252:253], v[232:233], v[150:151], v[252:253]
	v_cvt_pk_f32_fp8_e32 v[218:219], v98
	v_cvt_pk_f32_fp8_e32 v[226:227], v102
	v_cvt_pk_f32_fp8_sdwa v[220:221], v98 src0_sel:WORD_1
	v_cvt_pk_f32_fp8_sdwa v[228:229], v102 src0_sel:WORD_1
	v_cvt_pk_f32_fp8_e32 v[222:223], v99
	v_cvt_pk_f32_fp8_e32 v[230:231], v103
	v_cvt_pk_f32_fp8_sdwa v[224:225], v99 src0_sel:WORD_1
	v_cvt_pk_f32_fp8_sdwa v[232:233], v103 src0_sel:WORD_1
	v_pk_fma_f32 v[250:251], v[218:219], v[152:153], v[250:251]
	v_pk_fma_f32 v[252:253], v[226:227], v[152:153], v[252:253]
	v_pk_fma_f32 v[250:251], v[220:221], v[154:155], v[250:251]
	v_pk_fma_f32 v[252:253], v[228:229], v[154:155], v[252:253]
	v_pk_fma_f32 v[250:251], v[222:223], v[156:157], v[250:251]
	v_pk_fma_f32 v[252:253], v[230:231], v[156:157], v[252:253]
	v_pk_fma_f32 v[250:251], v[224:225], v[158:159], v[250:251]
	v_pk_fma_f32 v[252:253], v[232:233], v[158:159], v[252:253]
	v_add_f32_e32 v210, v250, v251
	v_add_f32_e32 v211, v252, v253
	v_cvt_pk_f32_fp8_e32 v[218:219], v104
	v_cvt_pk_f32_fp8_e32 v[226:227], v108
	v_cvt_pk_f32_fp8_sdwa v[220:221], v104 src0_sel:WORD_1
	v_cvt_pk_f32_fp8_sdwa v[228:229], v108 src0_sel:WORD_1
	v_cvt_pk_f32_fp8_e32 v[222:223], v105
	v_cvt_pk_f32_fp8_e32 v[230:231], v109
	v_cvt_pk_f32_fp8_sdwa v[224:225], v105 src0_sel:WORD_1
	v_cvt_pk_f32_fp8_sdwa v[232:233], v109 src0_sel:WORD_1
	v_pk_mul_f32 v[250:251], v[218:219], v[144:145]
	v_pk_mul_f32 v[252:253], v[226:227], v[144:145]
	v_pk_fma_f32 v[250:251], v[220:221], v[146:147], v[250:251]
	v_pk_fma_f32 v[252:253], v[228:229], v[146:147], v[252:253]
	v_pk_fma_f32 v[250:251], v[222:223], v[148:149], v[250:251]
	v_pk_fma_f32 v[252:253], v[230:231], v[148:149], v[252:253]
	v_pk_fma_f32 v[250:251], v[224:225], v[150:151], v[250:251]
	v_pk_fma_f32 v[252:253], v[232:233], v[150:151], v[252:253]
	v_cvt_pk_f32_fp8_e32 v[218:219], v106
	v_cvt_pk_f32_fp8_e32 v[226:227], v110
	v_cvt_pk_f32_fp8_sdwa v[220:221], v106 src0_sel:WORD_1
	v_cvt_pk_f32_fp8_sdwa v[228:229], v110 src0_sel:WORD_1
	v_cvt_pk_f32_fp8_e32 v[222:223], v107
	v_cvt_pk_f32_fp8_e32 v[230:231], v111
	v_cvt_pk_f32_fp8_sdwa v[224:225], v107 src0_sel:WORD_1
	v_cvt_pk_f32_fp8_sdwa v[232:233], v111 src0_sel:WORD_1
	v_pk_fma_f32 v[250:251], v[218:219], v[152:153], v[250:251]
	v_pk_fma_f32 v[252:253], v[226:227], v[152:153], v[252:253]
	v_pk_fma_f32 v[250:251], v[220:221], v[154:155], v[250:251]
	v_pk_fma_f32 v[252:253], v[228:229], v[154:155], v[252:253]
	v_pk_fma_f32 v[250:251], v[222:223], v[156:157], v[250:251]
	v_pk_fma_f32 v[252:253], v[230:231], v[156:157], v[252:253]
	v_pk_fma_f32 v[250:251], v[224:225], v[158:159], v[250:251]
	v_pk_fma_f32 v[252:253], v[232:233], v[158:159], v[252:253]
	v_add_f32_e32 v212, v250, v251
	v_add_f32_e32 v213, v252, v253
	v_cvt_pk_f32_fp8_e32 v[218:219], v112
	v_cvt_pk_f32_fp8_e32 v[226:227], v116
	v_cvt_pk_f32_fp8_sdwa v[220:221], v112 src0_sel:WORD_1
	v_cvt_pk_f32_fp8_sdwa v[228:229], v116 src0_sel:WORD_1
	v_cvt_pk_f32_fp8_e32 v[222:223], v113
	v_cvt_pk_f32_fp8_e32 v[230:231], v117
	v_cvt_pk_f32_fp8_sdwa v[224:225], v113 src0_sel:WORD_1
	v_cvt_pk_f32_fp8_sdwa v[232:233], v117 src0_sel:WORD_1
	v_pk_mul_f32 v[250:251], v[218:219], v[144:145]
	v_pk_mul_f32 v[252:253], v[226:227], v[144:145]
	v_pk_fma_f32 v[250:251], v[220:221], v[146:147], v[250:251]
	v_pk_fma_f32 v[252:253], v[228:229], v[146:147], v[252:253]
	v_pk_fma_f32 v[250:251], v[222:223], v[148:149], v[250:251]
	v_pk_fma_f32 v[252:253], v[230:231], v[148:149], v[252:253]
	v_pk_fma_f32 v[250:251], v[224:225], v[150:151], v[250:251]
	v_pk_fma_f32 v[252:253], v[232:233], v[150:151], v[252:253]
	v_cvt_pk_f32_fp8_e32 v[218:219], v114
	v_cvt_pk_f32_fp8_e32 v[226:227], v118
	v_cvt_pk_f32_fp8_sdwa v[220:221], v114 src0_sel:WORD_1
	v_cvt_pk_f32_fp8_sdwa v[228:229], v118 src0_sel:WORD_1
	v_cvt_pk_f32_fp8_e32 v[222:223], v115
	v_cvt_pk_f32_fp8_e32 v[230:231], v119
	v_cvt_pk_f32_fp8_sdwa v[224:225], v115 src0_sel:WORD_1
	v_cvt_pk_f32_fp8_sdwa v[232:233], v119 src0_sel:WORD_1
	v_pk_fma_f32 v[250:251], v[218:219], v[152:153], v[250:251]
	v_pk_fma_f32 v[252:253], v[226:227], v[152:153], v[252:253]
	v_pk_fma_f32 v[250:251], v[220:221], v[154:155], v[250:251]
	v_pk_fma_f32 v[252:253], v[228:229], v[154:155], v[252:253]
	v_pk_fma_f32 v[250:251], v[222:223], v[156:157], v[250:251]
	v_pk_fma_f32 v[252:253], v[230:231], v[156:157], v[252:253]
	v_pk_fma_f32 v[250:251], v[224:225], v[158:159], v[250:251]
	v_pk_fma_f32 v[252:253], v[232:233], v[158:159], v[252:253]
	v_add_f32_e32 v214, v250, v251
	v_add_f32_e32 v215, v252, v253
	v_cvt_pk_f32_fp8_e32 v[218:219], v120
	v_cvt_pk_f32_fp8_e32 v[226:227], v124
	v_cvt_pk_f32_fp8_sdwa v[220:221], v120 src0_sel:WORD_1
	v_cvt_pk_f32_fp8_sdwa v[228:229], v124 src0_sel:WORD_1
	v_cvt_pk_f32_fp8_e32 v[222:223], v121
	v_cvt_pk_f32_fp8_e32 v[230:231], v125
	v_cvt_pk_f32_fp8_sdwa v[224:225], v121 src0_sel:WORD_1
	v_cvt_pk_f32_fp8_sdwa v[232:233], v125 src0_sel:WORD_1
	v_pk_mul_f32 v[250:251], v[218:219], v[144:145]
	v_pk_mul_f32 v[252:253], v[226:227], v[144:145]
	v_pk_fma_f32 v[250:251], v[220:221], v[146:147], v[250:251]
	v_pk_fma_f32 v[252:253], v[228:229], v[146:147], v[252:253]
	v_pk_fma_f32 v[250:251], v[222:223], v[148:149], v[250:251]
	v_pk_fma_f32 v[252:253], v[230:231], v[148:149], v[252:253]
	v_pk_fma_f32 v[250:251], v[224:225], v[150:151], v[250:251]
	v_pk_fma_f32 v[252:253], v[232:233], v[150:151], v[252:253]
	v_cvt_pk_f32_fp8_e32 v[218:219], v122
	v_cvt_pk_f32_fp8_e32 v[226:227], v126
	v_cvt_pk_f32_fp8_sdwa v[220:221], v122 src0_sel:WORD_1
	v_cvt_pk_f32_fp8_sdwa v[228:229], v126 src0_sel:WORD_1
	v_cvt_pk_f32_fp8_e32 v[222:223], v123
	v_cvt_pk_f32_fp8_e32 v[230:231], v127
	v_cvt_pk_f32_fp8_sdwa v[224:225], v123 src0_sel:WORD_1
	v_cvt_pk_f32_fp8_sdwa v[232:233], v127 src0_sel:WORD_1
	v_pk_fma_f32 v[250:251], v[218:219], v[152:153], v[250:251]
	v_pk_fma_f32 v[252:253], v[226:227], v[152:153], v[252:253]
	v_pk_fma_f32 v[250:251], v[220:221], v[154:155], v[250:251]
	v_pk_fma_f32 v[252:253], v[228:229], v[154:155], v[252:253]
	v_pk_fma_f32 v[250:251], v[222:223], v[156:157], v[250:251]
	v_pk_fma_f32 v[252:253], v[230:231], v[156:157], v[252:253]
	v_pk_fma_f32 v[250:251], v[224:225], v[158:159], v[250:251]
	v_pk_fma_f32 v[252:253], v[232:233], v[158:159], v[252:253]
	v_add_f32_e32 v216, v250, v251
	v_add_f32_e32 v217, v252, v253
	s_lshl_b32 s34, s20, 9
	s_add_u32 s32, s12, s34
	s_addc_u32 s33, s13, 0
	s_nop 1
	v_add_f32_dpp v218, v202, v202 row_half_mirror row_mask:0xf bank_mask:0x5
	v_add_f32_dpp v219, v203, v203 row_half_mirror row_mask:0xf bank_mask:0x5
	v_add_f32_dpp v220, v204, v204 row_half_mirror row_mask:0xf bank_mask:0x5
	v_add_f32_dpp v221, v205, v205 row_half_mirror row_mask:0xf bank_mask:0x5
	v_add_f32_dpp v222, v206, v206 row_half_mirror row_mask:0xf bank_mask:0x5
	v_add_f32_dpp v223, v207, v207 row_half_mirror row_mask:0xf bank_mask:0x5
	v_add_f32_dpp v224, v208, v208 row_half_mirror row_mask:0xf bank_mask:0x5
	v_add_f32_dpp v225, v209, v209 row_half_mirror row_mask:0xf bank_mask:0x5
	v_add_f32_dpp v218, v210, v210 row_half_mirror row_mask:0xf bank_mask:0xa
	v_add_f32_dpp v219, v211, v211 row_half_mirror row_mask:0xf bank_mask:0xa
	v_add_f32_dpp v220, v212, v212 row_half_mirror row_mask:0xf bank_mask:0xa
	v_add_f32_dpp v221, v213, v213 row_half_mirror row_mask:0xf bank_mask:0xa
	v_add_f32_dpp v222, v214, v214 row_half_mirror row_mask:0xf bank_mask:0xa
	v_add_f32_dpp v223, v215, v215 row_half_mirror row_mask:0xf bank_mask:0xa
	v_add_f32_dpp v224, v216, v216 row_half_mirror row_mask:0xf bank_mask:0xa
	v_add_f32_dpp v225, v217, v217 row_half_mirror row_mask:0xf bank_mask:0xa
	v_cndmask_b32_e64 v226, v218, v222, s[26:27]
	v_cndmask_b32_e64 v227, v219, v223, s[26:27]
	v_cndmask_b32_e64 v228, v220, v224, s[26:27]
	v_cndmask_b32_e64 v229, v221, v225, s[26:27]
	v_cndmask_b32_e64 v230, v222, v218, s[26:27]
	v_cndmask_b32_e64 v231, v223, v219, s[26:27]
	v_cndmask_b32_e64 v232, v224, v220, s[26:27]
	v_cndmask_b32_e64 v233, v225, v221, s[26:27]
	s_nop 0
	v_add_f32_dpp v250, v230, v226 quad_perm:[2,3,0,1] row_mask:0xf bank_mask:0xf
	v_add_f32_dpp v251, v231, v227 quad_perm:[2,3,0,1] row_mask:0xf bank_mask:0xf
	v_add_f32_dpp v252, v232, v228 quad_perm:[2,3,0,1] row_mask:0xf bank_mask:0xf
	v_add_f32_dpp v253, v233, v229 quad_perm:[2,3,0,1] row_mask:0xf bank_mask:0xf
	v_cndmask_b32_e64 v226, v250, v252, s[28:29]
	v_cndmask_b32_e64 v227, v251, v253, s[28:29]
	v_cndmask_b32_e64 v230, v252, v250, s[28:29]
	v_cndmask_b32_e64 v231, v253, v251, s[28:29]
	s_nop 1
	v_add_f32_dpp v218, v230, v226 quad_perm:[1,0,3,2] row_mask:0xf bank_mask:0xf
	v_add_f32_dpp v219, v231, v227 quad_perm:[1,0,3,2] row_mask:0xf bank_mask:0xf
	global_store_dwordx2 v180, v[218:219], s[32:33]
	s_add_u32 s20, s20, s21
	s_cmp_lt_u32 s20, 0x4000
	s_cbranch_scc1 .Lgd_loop_L0
.Lgd_done_L0:
	s_waitcnt vmcnt(0)
	s_branch .LBB0_541

.LBB0_1117:
	s_or_b64 exec, exec, s[0:1]
	s_waitcnt lgkmcnt(0)
	v_mov_b32_e32 v0, v178
	s_barrier
	v_readlane_b32 s2, v255, 3
	v_ashrrev_i32_e32 v1, 6, v0
	s_movk_i32 s16, 0x4000
	v_add_u32_e32 v152, s2, v1
	s_mov_b64 s[6:7], 0
	s_mov_b64 s[0:1], 0
	v_cmp_gt_i32_e32 vcc, s16, v152
	s_and_saveexec_b64 s[8:9], vcc
	s_cbranch_execz .LBB0_1126
	v_readlane_b32 s0, v254, 0
	v_readlane_b32 s1, v254, 1
	v_readlane_b32 s34, v255, 4
	s_lshl_b32 s35, s34, 21
	s_add_u32 s2, s0, 0x4120000
	s_addc_u32 s3, s1, 0
	s_add_u32 s2, s2, s35
	s_addc_u32 s3, s3, 0
	v_readlane_b32 s4, v254, 39
	v_readlane_b32 s5, v254, 40
	s_lshl_b32 s35, s34, 9
	s_add_u32 s4, s4, s35
	s_addc_u32 s5, s5, 0
	s_add_u32 s6, s0, 0x19d20000
	s_addc_u32 s7, s1, 0
	s_lshl_b32 s35, s34, 23
	s_add_u32 s12, s0, 0x10120000
	s_addc_u32 s13, s1, 0
	s_add_u32 s12, s12, s35
	s_addc_u32 s13, s13, 0
	v_readfirstlane_b32 s20, v178
	s_lshr_b32 s20, s20, 6
	v_readlane_b32 s35, v255, 3
	s_add_u32 s20, s20, s35
	s_and_b32 s21, s90, -8
	v_and_b32_e32 v176, 7, v179
	v_lshlrev_b32_e32 v177, 6, v176
	v_lshlrev_b32_e32 v176, 4, v176
	v_lshlrev_b32_e32 v180, 3, v179
	v_lshrrev_b32_e32 v181, 3, v179
	v_lshlrev_b32_e32 v181, 6, v181
	s_mov_b32 s26, 0xcccccccc
	s_mov_b32 s27, 0xcccccccc
	s_mov_b32 s28, 0xaaaaaaaa
	s_mov_b32 s29, 0xaaaaaaaa
	s_lshl_b32 s34, s20, 9
	s_add_u32 s22, s6, s34
	s_addc_u32 s23, s7, 0
	global_load_dwordx4 v[160:163], v181, s[22:23] offset:0
	global_load_dwordx4 v[164:167], v181, s[22:23] offset:16
	global_load_dwordx4 v[168:171], v181, s[22:23] offset:32
	global_load_dwordx4 v[172:175], v181, s[22:23] offset:48
	s_add_u32 s36, s20, s21
	s_min_u32 s36, s36, 0x3fff
	s_lshl_b32 s34, s36, 9
	s_add_u32 s22, s6, s34
	s_addc_u32 s23, s7, 0
	global_load_dwordx4 v[186:189], v181, s[22:23] offset:0
	global_load_dwordx4 v[190:193], v181, s[22:23] offset:16
	global_load_dwordx4 v[194:197], v181, s[22:23] offset:32
	global_load_dwordx4 v[198:201], v181, s[22:23] offset:48
	s_waitcnt vmcnt(0)
	v_lshl_or_b32 v160, v160, 7, v176
	v_lshl_or_b32 v161, v161, 7, v176
	v_lshl_or_b32 v162, v162, 7, v176
	v_lshl_or_b32 v163, v163, 7, v176
	v_lshl_or_b32 v164, v164, 7, v176
	v_lshl_or_b32 v165, v165, 7, v176
	v_lshl_or_b32 v166, v166, 7, v176
	v_lshl_or_b32 v167, v167, 7, v176
	v_lshl_or_b32 v168, v168, 7, v176
	v_lshl_or_b32 v169, v169, 7, v176
	v_lshl_or_b32 v170, v170, 7, v176
	v_lshl_or_b32 v171, v171, 7, v176
	v_lshl_or_b32 v172, v172, 7, v176
	v_lshl_or_b32 v173, v173, 7, v176
	v_lshl_or_b32 v174, v174, 7, v176
	v_lshl_or_b32 v175, v175, 7, v176
	s_lshl_b32 s34, s20, 12
	s_add_u32 s24, s4, s34
	s_addc_u32 s25, s5, 0
	global_load_dwordx4 v[128:131], v177, s[24:25] offset:0
	global_load_dwordx4 v[132:135], v177, s[24:25] offset:16
	global_load_dwordx4 v[136:139], v177, s[24:25] offset:32
	global_load_dwordx4 v[140:143], v177, s[24:25] offset:48
	global_load_dwordx4 v[0:3], v160, s[2:3]
	global_load_dwordx4 v[4:7], v161, s[2:3]
	global_load_dwordx4 v[8:11], v162, s[2:3]
	global_load_dwordx4 v[12:15], v163, s[2:3]
	global_load_dwordx4 v[16:19], v164, s[2:3]
	global_load_dwordx4 v[20:23], v165, s[2:3]
	global_load_dwordx4 v[24:27], v166, s[2:3]
	global_load_dwordx4 v[28:31], v167, s[2:3]
	global_load_dwordx4 v[32:35], v168, s[2:3]
	global_load_dwordx4 v[36:39], v169, s[2:3]
	global_load_dwordx4 v[40:43], v170, s[2:3]
	global_load_dwordx4 v[44:47], v171, s[2:3]
	global_load_dwordx4 v[48:51], v172, s[2:3]
	global_load_dwordx4 v[52:55], v173, s[2:3]
	global_load_dwordx4 v[56:59], v174, s[2:3]
	global_load_dwordx4 v[60:63], v175, s[2:3]
	s_add_u32 s37, s36, s21
	s_min_u32 s37, s37, 0x3fff
	s_lshl_b32 s34, s37, 9
	s_add_u32 s22, s6, s34
	s_addc_u32 s23, s7, 0
	global_load_dwordx4 v[234:237], v181, s[22:23] offset:0
	global_load_dwordx4 v[238:241], v181, s[22:23] offset:16
	global_load_dwordx4 v[242:245], v181, s[22:23] offset:32
	global_load_dwordx4 v[246:249], v181, s[22:23] offset:48
	global_load_dword v250, v180, s[22:23]
